# NSA phase: per-MFMA-group s_setprio toggles removed, one static priority raise for waves 4-7 (re-padded hazards), on top of v21
# baseline (speedup 1.0000x reference)
; __device__ __forceinline__ void run_phase(const Params& P, int ph, char* lds) {
;     ...
;       nsa_tables(P, blockIdx.x & 1, lds);
;       for (int it = blockIdx.x; it < 1024; it += gridDim.x) {
;         const int rnd = it / 256, pos = it % 256;
;         const int c = (rnd & 1) ? (rnd >> 1) * 16 + (pos >> 4) : 63 - (rnd >> 1) * 16 - (pos >> 4);
;         const int bg = pos & 15;
;         nsa_item(P, bg >> 1, bg & 1, c, big, kcv, abuf, lds);
.LBB0_190:
	s_or_b64 exec, exec, s[0:1]
	v_readlane_b32 s0, v253, 1
	v_readlane_b32 s1, v253, 2
	s_andn2_b64 vcc, exec, s[0:1]
	s_waitcnt lgkmcnt(0)
	s_barrier
	s_cbranch_vccnz .LBB0_498
	v_readfirstlane_b32 s0, v179
	s_cmpk_lt_u32 s0, 0x100
	s_cbranch_scc1 .Lmy_prio
	s_setprio 1
.Lmy_prio:
	v_writelane_b32 v255, s84, 8
	s_mov_b32 s1, s2
	s_nop 0
	v_writelane_b32 v255, s85, 9
	s_branch .LBB0_193

; template <int MODE>
; __device__ __forceinline__ void nsa_compute(int cur, int buf, int t, int hl, u64 mymask, const bf16x8 (&Qf)[2][2], f32x4 (&O)[4][2], float (&m)[2], float (&l)[2],
;                                             const float (&inv)[2], float* impw, char* lds) {
;     ...
; #pragma unroll
;     for (int ks = 0; ks < 2; ++ks)
; #pragma unroll
;       for (int kk = 0; kk < 2; ++kk) kfr[ks][kk] = *(const bf16x8*)(kt + (32 * s2 + 16 * kk + fr) * 128 + (((ks * 4 + fq) ^ (fr & 7)) << 4));
;     __builtin_amdgcn_s_setprio(1);
; #pragma unroll
;     for (int ks = 0; ks < 2; ++ks)
; #pragma unroll
;       for (int kk = 0; kk < 2; ++kk)
; #pragma unroll
;         for (int r = 0; r < 2; ++r) S[kk][r] = mfma16(kfr[ks][kk], Qf[r][ks], S[kk][r]);
;     __builtin_amdgcn_s_setprio(0);
;     bf16x8 Pf[2];
;     float g1s[2] = {0.f, 0.f}, p3s[2] = {0.f, 0.f};
; #pragma unroll
;     for (int r = 0; r < 2; ++r) {
;       float sv[2][4];
; #pragma unroll
;       for (int kk = 0; kk < 2; ++kk)
; #pragma unroll
;         for (int e = 0; e < 4; ++e) {
;           const int off = 32 * s2 + 16 * kk + e;
;           int idx;
;           if (MODE <= 1) { idx = base - 16 * off; idx = idx > 0 ? idx : 0; } else idx = base - off;
;           sv[kk][e] = S[kk][r][e] * (0.125f * LOG2E) + tb[r * TS + idx];
;         }
;       float pv[2][4];
;       if (MODE == 1) {
; #pragma unroll
;         for (int kk = 0; kk < 2; ++kk)
; #pragma unroll
;           for (int e = 0; e < 4; ++e) pv[kk][e] = __builtin_amdgcn_exp2f(sv[kk][e] - m[r]) * inv[r];
; #pragma unroll
;         for (int kk = 0; kk < 2; ++kk) { g1s[kk] += pv[kk][0] + pv[kk][1] + pv[kk][2] + 0.5f * pv[kk][3]; p3s[kk] += 0.5f * pv[kk][3]; }
;       } else {
;         const float mxa = fmaxf(fmaxf(sv[0][0], sv[0][1]), sv[0][2]), mxb = fmaxf(fmaxf(sv[0][3], sv[1][0]), sv[1][1]);
;         float mx = fmaxf(fmaxf(fmaxf(sv[1][2], sv[1][3]), mxa), mxb);
;         if (MODE == 2) mx = selok ? mx : -__builtin_inff();
;         if (__any(mx > m[r] + 8.0f)) {
;           mx = fmaxf(mx, __shfl_xor(mx, 16)); mx = fmaxf(mx, __shfl_xor(mx, 32));
;           const float mn = fmaxf(m[r], mx), al = __builtin_amdgcn_exp2f(m[r] - mn);
;           m[r] = mn; l[r] *= al;
;           if (MODE != 0) {
; #pragma unroll
;             for (int df = 0; df < 4; ++df) O[df][r] *= al;
;           }
.LBB0_211:
	v_mov_b32 v72, v179
	s_lshl_b32 s72, s73, 13
	v_lshrrev_b32_e32 v73, 4, v72
	v_bfe_u32 v82, v72, 4, 2
	v_and_b32_e32 v83, 7, v72
	v_lshlrev_b32_e32 v72, 7, v72
	v_lshlrev_b32_e32 v74, 6, v82
	v_and_b32_e32 v87, 0x780, v72
	v_bitop3_b32 v72, v73, v83, 3 bitop3:0x6c
	v_bitop3_b32 v82, v82, v83, 4 bitop3:0x36
	s_mov_b32 s30, s69
	v_lshl_or_b32 v88, v72, 4, s72
	v_lshl_or_b32 v89, v82, 4, s72
	v_lshl_or_b32 v74, s30, 10, v74
	v_or_b32_e32 v76, v88, v87
	v_or_b32_e32 v90, v89, v87
	v_sub_u32_e32 v86, v183, v74
	ds_read_b128 v[72:75], v76
	ds_read_b128 v[76:79], v76 offset:2048
	ds_read_b128 v[82:85], v90
	ds_read_b128 v[90:93], v90 offset:2048
	s_mov_b32 s69, s31
	s_waitcnt vmcnt(3) lgkmcnt(3)
	v_mfma_f32_16x16x32_bf16 v[94:97], v[72:75], v[0:3], 0
	s_waitcnt vmcnt(1)
	v_mfma_f32_16x16x32_bf16 v[72:75], v[72:75], v[8:11], 0
	s_waitcnt lgkmcnt(2)
	v_mfma_f32_16x16x32_bf16 v[98:101], v[76:79], v[0:3], 0
	v_mfma_f32_16x16x32_bf16 v[102:105], v[76:79], v[8:11], 0
	s_waitcnt lgkmcnt(1)
	v_mfma_f32_16x16x32_bf16 v[106:109], v[82:85], v[4:7], v[94:97]
	s_waitcnt vmcnt(0)
	v_mfma_f32_16x16x32_bf16 v[76:79], v[82:85], v[12:15], v[72:75]
	s_waitcnt lgkmcnt(0)
	v_mfma_f32_16x16x32_bf16 v[82:85], v[90:93], v[4:7], v[98:101]
	v_mfma_f32_16x16x32_bf16 v[72:75], v[90:93], v[12:15], v[102:105]
	v_add_u32_e32 v91, -16, v86
	v_subrev_u32_e32 v92, 32, v86
	v_subrev_u32_e32 v93, 48, v86
	v_add_u32_e32 v94, 0xffffff00, v86
	v_max_i32_e32 v90, 0, v86
	v_max_i32_e32 v91, 0, v91
	v_max_i32_e32 v92, 0, v92
	v_max_i32_e32 v93, 0, v93
	v_max_i32_e32 v94, 0, v94
	v_lshl_add_u32 v90, v90, 2, v181
	v_lshl_add_u32 v91, v91, 2, v181
	v_lshl_add_u32 v92, v92, 2, v181
	v_lshl_add_u32 v93, v93, 2, v181
	v_lshl_add_u32 v94, v94, 2, v181
	ds_read_b32 v95, v90 offset:33792
	ds_read_b32 v97, v91 offset:33792
	ds_read_b32 v99, v92 offset:33792
	ds_read_b32 v101, v93 offset:33792
	ds_read_b32 v102, v94 offset:33792
	s_waitcnt lgkmcnt(4)
	v_fmac_f32_e32 v95, 0x3e38aa3b, v106
	s_waitcnt lgkmcnt(3)
	v_fmac_f32_e32 v97, 0x3e38aa3b, v107
	s_waitcnt lgkmcnt(2)
	v_fmac_f32_e32 v99, 0x3e38aa3b, v108
	s_waitcnt lgkmcnt(1)
	v_fmac_f32_e32 v101, 0x3e38aa3b, v109
	s_waitcnt lgkmcnt(0)
	v_fmac_f32_e32 v102, 0x3e38aa3b, v82
	v_add_u32_e32 v82, 0xfffffef0, v86
	v_max_i32_e32 v82, 0, v82
	v_lshl_add_u32 v96, v82, 2, v181
	v_add_u32_e32 v82, 0xfffffee0, v86
	v_max_i32_e32 v82, 0, v82
	v_lshl_add_u32 v98, v82, 2, v181
	v_add_u32_e32 v82, 0xfffffed0, v86
	v_max_i32_e32 v82, 0, v82
	v_lshl_add_u32 v100, v82, 2, v181
	ds_read_b32 v103, v96 offset:33792
	ds_read_b32 v104, v98 offset:33792
	ds_read_b32 v105, v100 offset:33792
	v_max3_f32 v82, v95, v97, v99
	s_waitcnt lgkmcnt(2)
	v_fmac_f32_e32 v103, 0x3e38aa3b, v83
	s_waitcnt lgkmcnt(1)
	v_fmac_f32_e32 v104, 0x3e38aa3b, v84
	s_waitcnt lgkmcnt(0)
	v_fmac_f32_e32 v105, 0x3e38aa3b, v85
	v_max3_f32 v83, v101, v102, v103
	v_max_f32_e32 v84, v104, v105
	v_max3_f32 v82, v84, v82, v83
	v_add_f32_e32 v83, 0x41000000, v154
	v_cmp_gt_f32_e32 vcc, v82, v83
	s_cbranch_vccz .LBB0_263
	v_cmp_lt_i32_e32 vcc, v220, v218
	s_nop 1
	v_cndmask_b32_e32 v83, v212, v220, vcc
	v_lshlrev_b32_e32 v83, 2, v83
	ds_bpermute_b32 v83, v83, v82
	v_cmp_lt_i32_e32 vcc, v219, v218
	v_max_f32_e32 v82, v82, v82
	s_waitcnt lgkmcnt(0)
	v_max_f32_e32 v83, v83, v83
	v_cndmask_b32_e32 v84, v212, v219, vcc
	v_max_f32_e32 v82, v82, v83
	v_lshlrev_b32_e32 v83, 2, v84
	ds_bpermute_b32 v83, v83, v82
	s_waitcnt lgkmcnt(0)
	v_max3_f32 v82, v154, v82, v83
	v_sub_f32_e32 v83, v154, v82
	v_exp_f32_e32 v84, v83
	v_mov_b32_e32 v83, v155
	v_mul_f32_e32 v80, v80, v84
	v_mov_b64_e32 v[84:85], v[82:83]
	s_cbranch_execnz .LBB0_214

; template <int MODE>
; __device__ __forceinline__ void nsa_compute(int cur, int buf, int t, int hl, u64 mymask, const bf16x8 (&Qf)[2][2], f32x4 (&O)[4][2], float (&m)[2], float (&l)[2],
;                                             const float (&inv)[2], float* impw, char* lds) {
;     ...
; #pragma unroll
;     for (int ks = 0; ks < 2; ++ks)
; #pragma unroll
;       for (int kk = 0; kk < 2; ++kk) kfr[ks][kk] = *(const bf16x8*)(kt + (32 * s2 + 16 * kk + fr) * 128 + (((ks * 4 + fq) ^ (fr & 7)) << 4));
;     __builtin_amdgcn_s_setprio(1);
; #pragma unroll
;     for (int ks = 0; ks < 2; ++ks)
; #pragma unroll
;       for (int kk = 0; kk < 2; ++kk)
; #pragma unroll
;         for (int r = 0; r < 2; ++r) S[kk][r] = mfma16(kfr[ks][kk], Qf[r][ks], S[kk][r]);
;     __builtin_amdgcn_s_setprio(0);
;     bf16x8 Pf[2];
;     float g1s[2] = {0.f, 0.f}, p3s[2] = {0.f, 0.f};
; #pragma unroll
;     for (int r = 0; r < 2; ++r) {
;       float sv[2][4];
; #pragma unroll
;       for (int kk = 0; kk < 2; ++kk)
; #pragma unroll
;         for (int e = 0; e < 4; ++e) {
;           const int off = 32 * s2 + 16 * kk + e;
;           int idx;
;           if (MODE <= 1) { idx = base - 16 * off; idx = idx > 0 ? idx : 0; } else idx = base - off;
;           sv[kk][e] = S[kk][r][e] * (0.125f * LOG2E) + tb[r * TS + idx];
;         }
;       float pv[2][4];
;       if (MODE == 1) {
; #pragma unroll
;         for (int kk = 0; kk < 2; ++kk)
; #pragma unroll
;           for (int e = 0; e < 4; ++e) pv[kk][e] = __builtin_amdgcn_exp2f(sv[kk][e] - m[r]) * inv[r];
; #pragma unroll
;         for (int kk = 0; kk < 2; ++kk) { g1s[kk] += pv[kk][0] + pv[kk][1] + pv[kk][2] + 0.5f * pv[kk][3]; p3s[kk] += 0.5f * pv[kk][3]; }
;       } else {
;         const float mxa = fmaxf(fmaxf(sv[0][0], sv[0][1]), sv[0][2]), mxb = fmaxf(fmaxf(sv[0][3], sv[1][0]), sv[1][1]);
;         float mx = fmaxf(fmaxf(fmaxf(sv[1][2], sv[1][3]), mxa), mxb);
;         if (MODE == 2) mx = selok ? mx : -__builtin_inff();
;         if (__any(mx > m[r] + 8.0f)) {
;           mx = fmaxf(mx, __shfl_xor(mx, 16)); mx = fmaxf(mx, __shfl_xor(mx, 32));
;           const float mn = fmaxf(m[r], mx), al = __builtin_amdgcn_exp2f(m[r] - mn);
;           m[r] = mn; l[r] *= al;
;           if (MODE != 0) {
; #pragma unroll
;             for (int df = 0; df < 4; ++df) O[df][r] *= al;
;           }
;         }
.LBB0_217:
	v_sub_f32_e32 v72, v101, v73
	v_exp_f32_e32 v72, v72
	v_sub_f32_e32 v74, v99, v73
	v_exp_f32_e32 v74, v74
	v_add_u32_e32 v76, v88, v87
	v_add_f32_e32 v72, 0, v72
	v_add_u32_e32 v84, v89, v87
	v_add_f32_e32 v72, v74, v72
	v_sub_f32_e32 v74, v97, v73
	v_exp_f32_e32 v74, v74
	s_nop 0
	v_add_f32_e32 v72, v74, v72
	v_sub_f32_e32 v74, v95, v73
	v_exp_f32_e32 v74, v74
	s_nop 0
	v_add_f32_e32 v72, v74, v72
	v_sub_f32_e32 v74, v93, v73
	v_exp_f32_e32 v74, v74
	s_nop 0
	v_add_f32_e32 v72, v74, v72
	v_sub_f32_e32 v74, v92, v73
	v_exp_f32_e32 v74, v74
	s_nop 0
	v_add_f32_e32 v72, v74, v72
	v_sub_f32_e32 v74, v91, v73
	v_exp_f32_e32 v74, v74
	v_sub_f32_e32 v73, v90, v73
	v_exp_f32_e32 v73, v73
	v_add_f32_e32 v72, v74, v72
	v_add_f32_e32 v72, v73, v72
	v_add_f32_e32 v81, v81, v72
	ds_read_b128 v[72:75], v76 offset:4096
	ds_read_b128 v[76:79], v76 offset:6144
	ds_read_b128 v[88:91], v84 offset:4096
	ds_read_b128 v[92:95], v84 offset:6144
	s_waitcnt lgkmcnt(3)
	v_mfma_f32_16x16x32_bf16 v[96:99], v[72:75], v[0:3], 0
	v_mfma_f32_16x16x32_bf16 v[72:75], v[72:75], v[8:11], 0
	s_waitcnt lgkmcnt(2)
	v_mfma_f32_16x16x32_bf16 v[104:107], v[76:79], v[8:11], 0
	v_mfma_f32_16x16x32_bf16 v[100:103], v[76:79], v[0:3], 0
	s_waitcnt lgkmcnt(1)
	v_mfma_f32_16x16x32_bf16 v[76:79], v[88:91], v[12:15], v[72:75]
	s_waitcnt lgkmcnt(0)
	v_mfma_f32_16x16x32_bf16 v[72:75], v[92:95], v[12:15], v[104:107]
	v_mfma_f32_16x16x32_bf16 v[108:111], v[88:91], v[4:7], v[96:99]
	v_mfma_f32_16x16x32_bf16 v[112:115], v[92:95], v[4:7], v[100:103]
	v_add_u32_e32 v84, 0xfffffe00, v86
	v_max_i32_e32 v84, 0, v84
	v_lshl_add_u32 v88, v84, 2, v181
	v_add_u32_e32 v84, 0xfffffdf0, v86
	v_max_i32_e32 v84, 0, v84
	v_lshl_add_u32 v89, v84, 2, v181
	v_add_u32_e32 v84, 0xfffffde0, v86
	v_max_i32_e32 v84, 0, v84
	v_lshl_add_u32 v90, v84, 2, v181
	v_add_u32_e32 v84, 0xfffffdd0, v86
	v_max_i32_e32 v84, 0, v84
	v_lshl_add_u32 v91, v84, 2, v181
	v_add_u32_e32 v84, 0xfffffd00, v86
	v_max_i32_e32 v84, 0, v84
	v_lshl_add_u32 v92, v84, 2, v181
	v_add_u32_e32 v84, 0xfffffcf0, v86
	v_max_i32_e32 v84, 0, v84
	v_lshl_add_u32 v94, v84, 2, v181
	v_add_u32_e32 v84, 0xfffffce0, v86
	v_max_i32_e32 v84, 0, v84
	v_lshl_add_u32 v96, v84, 2, v181
	v_add_u32_e32 v84, 0xfffffcd0, v86
	v_max_i32_e32 v84, 0, v84
	v_lshl_add_u32 v98, v84, 2, v181
	ds_read_b32 v93, v88 offset:33792
	ds_read_b32 v95, v89 offset:33792
	ds_read_b32 v97, v90 offset:33792
	ds_read_b32 v99, v91 offset:33792
	ds_read_b32 v100, v92 offset:33792
	ds_read_b32 v101, v94 offset:33792
	ds_read_b32 v102, v96 offset:33792
	ds_read_b32 v103, v98 offset:33792
	s_waitcnt lgkmcnt(7)
	v_fmac_f32_e32 v93, 0x3e38aa3b, v108
	s_waitcnt lgkmcnt(6)
	v_fmac_f32_e32 v95, 0x3e38aa3b, v109
	s_waitcnt lgkmcnt(5)
	v_fmac_f32_e32 v97, 0x3e38aa3b, v110
	s_waitcnt lgkmcnt(4)
	v_fmac_f32_e32 v99, 0x3e38aa3b, v111
	s_waitcnt lgkmcnt(3)
	v_fmac_f32_e32 v100, 0x3e38aa3b, v112
	s_waitcnt lgkmcnt(2)
	v_fmac_f32_e32 v101, 0x3e38aa3b, v113
	s_waitcnt lgkmcnt(1)
	v_fmac_f32_e32 v102, 0x3e38aa3b, v114
	s_waitcnt lgkmcnt(0)
	v_fmac_f32_e32 v103, 0x3e38aa3b, v115
	v_max3_f32 v84, v93, v95, v97
	v_max3_f32 v85, v99, v100, v101
	v_max_f32_e32 v86, v102, v103
	v_max3_f32 v84, v86, v84, v85
	v_add_f32_e32 v85, 0x41000000, v82
	v_cmp_gt_f32_e32 vcc, v84, v85
	s_cbranch_vccz .LBB0_265
	v_cmp_lt_i32_e32 vcc, v220, v218
	v_mov_b32_e32 v87, v83
	s_nop 0
	v_cndmask_b32_e32 v85, v212, v220, vcc
	v_lshlrev_b32_e32 v85, 2, v85
	ds_bpermute_b32 v85, v85, v84
	v_cmp_lt_i32_e32 vcc, v219, v218
	v_max_f32_e32 v84, v84, v84
	s_waitcnt lgkmcnt(0)
	v_max_f32_e32 v85, v85, v85
	v_cndmask_b32_e32 v86, v212, v219, vcc
	v_max_f32_e32 v84, v84, v85
	v_lshlrev_b32_e32 v85, 2, v86
	ds_bpermute_b32 v85, v85, v84
	s_waitcnt lgkmcnt(0)
	v_max3_f32 v86, v82, v84, v85
	v_sub_f32_e32 v84, v82, v86
	v_exp_f32_e32 v84, v84
	s_nop 0
	v_mul_f32_e32 v80, v80, v84
	v_mov_b64_e32 v[84:85], v[86:87]
	s_cbranch_execnz .LBB0_220

; template <int MODE>
; __device__ __forceinline__ void nsa_compute(int cur, int buf, int t, int hl, u64 mymask, const bf16x8 (&Qf)[2][2], f32x4 (&O)[4][2], float (&m)[2], float (&l)[2],
;                                             const float (&inv)[2], float* impw, char* lds) {
;     ...
; #pragma unroll
;     for (int ks = 0; ks < 2; ++ks)
; #pragma unroll
;       for (int kk = 0; kk < 2; ++kk) kfr[ks][kk] = *(const bf16x8*)(kt + (32 * s2 + 16 * kk + fr) * 128 + (((ks * 4 + fq) ^ (fr & 7)) << 4));
;     __builtin_amdgcn_s_setprio(1);
; #pragma unroll
;     for (int ks = 0; ks < 2; ++ks)
; #pragma unroll
;       for (int kk = 0; kk < 2; ++kk)
; #pragma unroll
;         for (int r = 0; r < 2; ++r) S[kk][r] = mfma16(kfr[ks][kk], Qf[r][ks], S[kk][r]);
;     __builtin_amdgcn_s_setprio(0);
;     bf16x8 Pf[2];
;     float g1s[2] = {0.f, 0.f}, p3s[2] = {0.f, 0.f};
; #pragma unroll
;     for (int r = 0; r < 2; ++r) {
;       float sv[2][4];
; #pragma unroll
;       for (int kk = 0; kk < 2; ++kk)
; #pragma unroll
;         for (int e = 0; e < 4; ++e) {
;           const int off = 32 * s2 + 16 * kk + e;
;           int idx;
;           if (MODE <= 1) { idx = base - 16 * off; idx = idx > 0 ? idx : 0; } else idx = base - off;
;           sv[kk][e] = S[kk][r][e] * (0.125f * LOG2E) + tb[r * TS + idx];
;         }
;       float pv[2][4];
;       if (MODE == 1) {
; #pragma unroll
;         for (int kk = 0; kk < 2; ++kk)
; #pragma unroll
;           for (int e = 0; e < 4; ++e) pv[kk][e] = __builtin_amdgcn_exp2f(sv[kk][e] - m[r]) * inv[r];
; #pragma unroll
;         for (int kk = 0; kk < 2; ++kk) { g1s[kk] += pv[kk][0] + pv[kk][1] + pv[kk][2] + 0.5f * pv[kk][3]; p3s[kk] += 0.5f * pv[kk][3]; }
;       } else {
;         const float mxa = fmaxf(fmaxf(sv[0][0], sv[0][1]), sv[0][2]), mxb = fmaxf(fmaxf(sv[0][3], sv[1][0]), sv[1][1]);
;         float mx = fmaxf(fmaxf(fmaxf(sv[1][2], sv[1][3]), mxa), mxb);
;         if (MODE == 2) mx = selok ? mx : -__builtin_inff();
;         if (__any(mx > m[r] + 8.0f)) {
;           mx = fmaxf(mx, __shfl_xor(mx, 16)); mx = fmaxf(mx, __shfl_xor(mx, 32));
;           const float mn = fmaxf(m[r], mx), al = __builtin_amdgcn_exp2f(m[r] - mn);
;           m[r] = mn; l[r] *= al;
;           if (MODE != 0) {
; #pragma unroll
;             for (int df = 0; df < 4; ++df) O[df][r] *= al;
;           }
;         }
.LBB0_227:
	v_sub_f32_e32 v72, v88, v73
	v_exp_f32_e32 v72, v72
	v_sub_f32_e32 v74, v89, v73
	v_exp_f32_e32 v74, v74
	v_sub_f32_e32 v75, v90, v73
	v_exp_f32_e32 v75, v75
	v_sub_f32_e32 v76, v91, v73
	v_exp_f32_e32 v76, v76
	v_add_f32_e32 v72, 0, v72
	v_add_f32_e32 v72, v74, v72
	v_sub_f32_e32 v74, v82, v73
	v_add_f32_e32 v72, v75, v72
	v_exp_f32_e32 v74, v74
	v_sub_f32_e32 v75, v83, v73
	v_add_f32_e32 v72, v76, v72
	v_exp_f32_e32 v75, v75
	v_sub_f32_e32 v76, v86, v73
	v_exp_f32_e32 v76, v76
	v_sub_f32_e32 v73, v87, v73
	v_exp_f32_e32 v73, v73
	v_add_f32_e32 v72, v74, v72
	v_add_f32_e32 v72, v75, v72
	v_add_f32_e32 v72, v76, v72
	v_add_f32_e32 v72, v73, v72
	v_add_f32_e32 v81, v81, v72
	s_cmp_lt_i32 s75, 0
	s_mov_b64 vcc, -1
	s_cbranch_scc1 .LBB0_262
	v_mov_b32 v72, v179
	s_lshl_b32 s74, s71, 13
	v_lshrrev_b32_e32 v73, 4, v72
	v_bfe_u32 v86, v72, 4, 2
	v_and_b32_e32 v82, 7, v72
	v_lshlrev_b32_e32 v72, 7, v72
	v_and_b32_e32 v87, 0x780, v72
	v_bitop3_b32 v72, v73, v82, 3 bitop3:0x6c
	v_bitop3_b32 v82, v86, v82, 4 bitop3:0x36
	v_lshl_or_b32 v88, v72, 4, s74
	v_lshl_or_b32 v89, v82, 4, s74
	v_or_b32_e32 v76, v88, v87
	v_or_b32_e32 v90, v89, v87
	ds_read_b128 v[72:75], v76
	ds_read_b128 v[76:79], v76 offset:2048
	ds_read_b128 v[82:85], v90
	ds_read_b128 v[90:93], v90 offset:2048
	v_lshlrev_b32_e32 v86, 6, v86
	v_lshl_or_b32 v86, s75, 10, v86
	v_sub_u32_e32 v86, v183, v86
	s_waitcnt lgkmcnt(3)
	v_mfma_f32_16x16x32_bf16 v[94:97], v[72:75], v[0:3], 0
	v_mfma_f32_16x16x32_bf16 v[72:75], v[72:75], v[8:11], 0
	s_waitcnt lgkmcnt(2)
	v_mfma_f32_16x16x32_bf16 v[98:101], v[76:79], v[0:3], 0
	v_mfma_f32_16x16x32_bf16 v[102:105], v[76:79], v[8:11], 0
	s_waitcnt lgkmcnt(1)
	v_mfma_f32_16x16x32_bf16 v[106:109], v[82:85], v[4:7], v[94:97]
	v_mfma_f32_16x16x32_bf16 v[76:79], v[82:85], v[12:15], v[72:75]
	s_waitcnt lgkmcnt(0)
	v_mfma_f32_16x16x32_bf16 v[82:85], v[90:93], v[4:7], v[98:101]
	v_mfma_f32_16x16x32_bf16 v[72:75], v[90:93], v[12:15], v[102:105]
	v_add_u32_e32 v91, -16, v86
	v_subrev_u32_e32 v92, 32, v86
	v_subrev_u32_e32 v93, 48, v86
	v_add_u32_e32 v94, 0xffffff00, v86
	v_max_i32_e32 v90, 0, v86
	v_max_i32_e32 v91, 0, v91
	v_max_i32_e32 v92, 0, v92
	v_max_i32_e32 v93, 0, v93
	v_max_i32_e32 v94, 0, v94
	v_lshl_add_u32 v90, v90, 2, v181
	v_lshl_add_u32 v91, v91, 2, v181
	v_lshl_add_u32 v92, v92, 2, v181
	v_lshl_add_u32 v93, v93, 2, v181
	v_lshl_add_u32 v94, v94, 2, v181
	ds_read_b32 v95, v90 offset:33792
	ds_read_b32 v97, v91 offset:33792
	ds_read_b32 v99, v92 offset:33792
	ds_read_b32 v101, v93 offset:33792
	ds_read_b32 v102, v94 offset:33792
	s_waitcnt lgkmcnt(4)
	v_fmac_f32_e32 v95, 0x3e38aa3b, v106
	s_waitcnt lgkmcnt(3)
	v_fmac_f32_e32 v97, 0x3e38aa3b, v107
	s_waitcnt lgkmcnt(2)
	v_fmac_f32_e32 v99, 0x3e38aa3b, v108
	s_waitcnt lgkmcnt(1)
	v_fmac_f32_e32 v101, 0x3e38aa3b, v109
	s_waitcnt lgkmcnt(0)
	v_fmac_f32_e32 v102, 0x3e38aa3b, v82
	v_add_u32_e32 v82, 0xfffffef0, v86
	v_max_i32_e32 v82, 0, v82
	v_lshl_add_u32 v96, v82, 2, v181
	v_add_u32_e32 v82, 0xfffffee0, v86
	v_max_i32_e32 v82, 0, v82
	v_lshl_add_u32 v98, v82, 2, v181
	v_add_u32_e32 v82, 0xfffffed0, v86
	v_max_i32_e32 v82, 0, v82
	v_lshl_add_u32 v100, v82, 2, v181
	ds_read_b32 v103, v96 offset:33792
	ds_read_b32 v104, v98 offset:33792
	ds_read_b32 v105, v100 offset:33792
	v_max3_f32 v82, v95, v97, v99
	s_waitcnt lgkmcnt(2)
	v_fmac_f32_e32 v103, 0x3e38aa3b, v83
	s_waitcnt lgkmcnt(1)
	v_fmac_f32_e32 v104, 0x3e38aa3b, v84
	s_waitcnt lgkmcnt(0)
	v_fmac_f32_e32 v105, 0x3e38aa3b, v85
	v_max3_f32 v83, v101, v102, v103
	v_max_f32_e32 v84, v104, v105
	v_max3_f32 v82, v84, v82, v83
	v_add_f32_e32 v83, 0x41000000, v154
	v_cmp_gt_f32_e32 vcc, v82, v83
	s_cbranch_vccz .LBB0_269
	v_cmp_lt_i32_e32 vcc, v220, v218
	s_nop 1
	v_cndmask_b32_e32 v83, v212, v220, vcc
	v_lshlrev_b32_e32 v83, 2, v83
	ds_bpermute_b32 v83, v83, v82
	v_cmp_lt_i32_e32 vcc, v219, v218
	v_max_f32_e32 v82, v82, v82
	s_waitcnt lgkmcnt(0)
	v_max_f32_e32 v83, v83, v83
	v_cndmask_b32_e32 v84, v212, v219, vcc
	v_max_f32_e32 v82, v82, v83
	v_lshlrev_b32_e32 v83, 2, v84
	ds_bpermute_b32 v83, v83, v82
	s_waitcnt lgkmcnt(0)
	v_max3_f32 v82, v154, v82, v83
	v_sub_f32_e32 v83, v154, v82
	v_exp_f32_e32 v84, v83
	v_mov_b32_e32 v83, v155
	v_mul_f32_e32 v80, v80, v84
	v_mov_b64_e32 v[84:85], v[82:83]
	s_cbranch_execnz .LBB0_231

; template <int MODE>
; __device__ __forceinline__ void nsa_compute(int cur, int buf, int t, int hl, u64 mymask, const bf16x8 (&Qf)[2][2], f32x4 (&O)[4][2], float (&m)[2], float (&l)[2],
;                                             const float (&inv)[2], float* impw, char* lds) {
;     ...
; #pragma unroll
;     for (int ks = 0; ks < 2; ++ks)
; #pragma unroll
;       for (int kk = 0; kk < 2; ++kk) kfr[ks][kk] = *(const bf16x8*)(kt + (32 * s2 + 16 * kk + fr) * 128 + (((ks * 4 + fq) ^ (fr & 7)) << 4));
;     __builtin_amdgcn_s_setprio(1);
; #pragma unroll
;     for (int ks = 0; ks < 2; ++ks)
; #pragma unroll
;       for (int kk = 0; kk < 2; ++kk)
; #pragma unroll
;         for (int r = 0; r < 2; ++r) S[kk][r] = mfma16(kfr[ks][kk], Qf[r][ks], S[kk][r]);
;     __builtin_amdgcn_s_setprio(0);
;     bf16x8 Pf[2];
;     float g1s[2] = {0.f, 0.f}, p3s[2] = {0.f, 0.f};
; #pragma unroll
;     for (int r = 0; r < 2; ++r) {
;       float sv[2][4];
; #pragma unroll
;       for (int kk = 0; kk < 2; ++kk)
; #pragma unroll
;         for (int e = 0; e < 4; ++e) {
;           const int off = 32 * s2 + 16 * kk + e;
;           int idx;
;           if (MODE <= 1) { idx = base - 16 * off; idx = idx > 0 ? idx : 0; } else idx = base - off;
;           sv[kk][e] = S[kk][r][e] * (0.125f * LOG2E) + tb[r * TS + idx];
;         }
;       float pv[2][4];
;       if (MODE == 1) {
; #pragma unroll
;         for (int kk = 0; kk < 2; ++kk)
; #pragma unroll
;           for (int e = 0; e < 4; ++e) pv[kk][e] = __builtin_amdgcn_exp2f(sv[kk][e] - m[r]) * inv[r];
; #pragma unroll
;         for (int kk = 0; kk < 2; ++kk) { g1s[kk] += pv[kk][0] + pv[kk][1] + pv[kk][2] + 0.5f * pv[kk][3]; p3s[kk] += 0.5f * pv[kk][3]; }
;       } else {
;         const float mxa = fmaxf(fmaxf(sv[0][0], sv[0][1]), sv[0][2]), mxb = fmaxf(fmaxf(sv[0][3], sv[1][0]), sv[1][1]);
;         float mx = fmaxf(fmaxf(fmaxf(sv[1][2], sv[1][3]), mxa), mxb);
;         if (MODE == 2) mx = selok ? mx : -__builtin_inff();
;         if (__any(mx > m[r] + 8.0f)) {
;           mx = fmaxf(mx, __shfl_xor(mx, 16)); mx = fmaxf(mx, __shfl_xor(mx, 32));
;           const float mn = fmaxf(m[r], mx), al = __builtin_amdgcn_exp2f(m[r] - mn);
;           m[r] = mn; l[r] *= al;
;           if (MODE != 0) {
; #pragma unroll
;             for (int df = 0; df < 4; ++df) O[df][r] *= al;
;           }
;         }
.LBB0_244:
	v_sub_f32_e32 v72, v88, v73
	v_exp_f32_e32 v72, v72
	v_sub_f32_e32 v74, v89, v73
	v_exp_f32_e32 v74, v74
	v_sub_f32_e32 v75, v90, v73
	v_exp_f32_e32 v75, v75
	v_sub_f32_e32 v76, v91, v73
	v_exp_f32_e32 v76, v76
	v_add_f32_e32 v72, 0, v72
	v_add_f32_e32 v72, v74, v72
	v_sub_f32_e32 v74, v82, v73
	v_add_f32_e32 v72, v75, v72
	v_exp_f32_e32 v74, v74
	v_sub_f32_e32 v75, v83, v73
	v_add_f32_e32 v72, v76, v72
	v_exp_f32_e32 v75, v75
	v_sub_f32_e32 v76, v86, v73
	v_exp_f32_e32 v76, v76
	v_sub_f32_e32 v73, v87, v73
	v_exp_f32_e32 v73, v73
	v_add_f32_e32 v72, v74, v72
	v_add_f32_e32 v72, v75, v72
	v_add_f32_e32 v72, v76, v72
	v_add_f32_e32 v72, v73, v72
	v_add_f32_e32 v81, v81, v72
	s_cmp_lt_i32 s43, 0
	s_mov_b64 vcc, -1
	s_cbranch_scc1 .LBB0_267
	v_mov_b32 v72, v179
	s_nop 0
	v_lshrrev_b32_e32 v73, 4, v72
	v_bfe_u32 v82, v72, 4, 2
	v_and_b32_e32 v83, 7, v72
	v_lshlrev_b32_e32 v72, 7, v72
	v_lshlrev_b32_e32 v74, 6, v82
	v_and_b32_e32 v84, 0x780, v72
	v_bitop3_b32 v72, v73, v83, 3 bitop3:0x6c
	v_bitop3_b32 v82, v82, v83, 4 bitop3:0x36
	v_lshl_add_u32 v72, v72, 4, s72
	v_lshl_add_u32 v82, v82, 4, s72
	v_lshl_or_b32 v74, s43, 10, v74
	v_add_u32_e32 v87, v72, v84
	v_add_u32_e32 v88, v82, v84
	v_sub_u32_e32 v86, v183, v74
	ds_read_b128 v[72:75], v87
	ds_read_b128 v[76:79], v87 offset:2048
	ds_read_b128 v[82:85], v88
	ds_read_b128 v[90:93], v88 offset:2048
	s_waitcnt lgkmcnt(3)
	v_mfma_f32_16x16x32_bf16 v[94:97], v[72:75], v[0:3], 0
	v_mfma_f32_16x16x32_bf16 v[72:75], v[72:75], v[8:11], 0
	s_waitcnt lgkmcnt(2)
	v_mfma_f32_16x16x32_bf16 v[98:101], v[76:79], v[0:3], 0
	v_mfma_f32_16x16x32_bf16 v[102:105], v[76:79], v[8:11], 0
	s_waitcnt lgkmcnt(1)
	v_mfma_f32_16x16x32_bf16 v[106:109], v[82:85], v[4:7], v[94:97]
	v_mfma_f32_16x16x32_bf16 v[76:79], v[82:85], v[12:15], v[72:75]
	s_waitcnt lgkmcnt(0)
	v_mfma_f32_16x16x32_bf16 v[82:85], v[90:93], v[4:7], v[98:101]
	v_mfma_f32_16x16x32_bf16 v[72:75], v[90:93], v[12:15], v[102:105]
	v_add_u32_e32 v90, -16, v86
	v_subrev_u32_e32 v91, 32, v86
	v_subrev_u32_e32 v92, 48, v86
	v_add_u32_e32 v93, 0xffffff00, v86
	v_max_i32_e32 v89, 0, v86
	v_max_i32_e32 v90, 0, v90
	v_max_i32_e32 v91, 0, v91
	v_max_i32_e32 v92, 0, v92
	v_max_i32_e32 v93, 0, v93
	v_lshl_add_u32 v89, v89, 2, v181
	v_lshl_add_u32 v90, v90, 2, v181
	v_lshl_add_u32 v91, v91, 2, v181
	v_lshl_add_u32 v92, v92, 2, v181
	v_lshl_add_u32 v93, v93, 2, v181
	ds_read_b32 v94, v89 offset:33792
	ds_read_b32 v96, v90 offset:33792
	ds_read_b32 v98, v91 offset:33792
	ds_read_b32 v100, v92 offset:33792
	ds_read_b32 v101, v93 offset:33792
	s_waitcnt lgkmcnt(4)
	v_fmac_f32_e32 v94, 0x3e38aa3b, v106
	s_waitcnt lgkmcnt(3)
	v_fmac_f32_e32 v96, 0x3e38aa3b, v107
	s_waitcnt lgkmcnt(2)
	v_fmac_f32_e32 v98, 0x3e38aa3b, v108
	s_waitcnt lgkmcnt(1)
	v_fmac_f32_e32 v100, 0x3e38aa3b, v109
	s_waitcnt lgkmcnt(0)
	v_fmac_f32_e32 v101, 0x3e38aa3b, v82
	v_add_u32_e32 v82, 0xfffffef0, v86
	v_max_i32_e32 v82, 0, v82
	v_lshl_add_u32 v95, v82, 2, v181
	v_add_u32_e32 v82, 0xfffffee0, v86
	v_max_i32_e32 v82, 0, v82
	v_lshl_add_u32 v97, v82, 2, v181
	v_add_u32_e32 v82, 0xfffffed0, v86
	v_max_i32_e32 v82, 0, v82
	v_lshl_add_u32 v99, v82, 2, v181
	ds_read_b32 v102, v95 offset:33792
	ds_read_b32 v103, v97 offset:33792
	ds_read_b32 v104, v99 offset:33792
	v_max3_f32 v82, v94, v96, v98
	s_waitcnt lgkmcnt(2)
	v_fmac_f32_e32 v102, 0x3e38aa3b, v83
	s_waitcnt lgkmcnt(1)
	v_fmac_f32_e32 v103, 0x3e38aa3b, v84
	s_waitcnt lgkmcnt(0)
	v_fmac_f32_e32 v104, 0x3e38aa3b, v85
	v_max3_f32 v83, v100, v101, v102
	v_max_f32_e32 v84, v103, v104
	v_max3_f32 v82, v84, v82, v83
	v_add_f32_e32 v83, 0x41000000, v154
	v_cmp_gt_f32_e32 vcc, v82, v83
	s_cbranch_vccz .LBB0_273
	v_cmp_lt_i32_e32 vcc, v220, v218
	s_nop 1
	v_cndmask_b32_e32 v83, v212, v220, vcc
	v_lshlrev_b32_e32 v83, 2, v83
	ds_bpermute_b32 v83, v83, v82
	v_cmp_lt_i32_e32 vcc, v219, v218
	v_max_f32_e32 v82, v82, v82
	s_waitcnt lgkmcnt(0)
	v_max_f32_e32 v83, v83, v83
	v_cndmask_b32_e32 v84, v212, v219, vcc
	v_max_f32_e32 v82, v82, v83
	v_lshlrev_b32_e32 v83, 2, v84
	ds_bpermute_b32 v83, v83, v82
	s_waitcnt lgkmcnt(0)
	v_max3_f32 v82, v154, v82, v83
	v_sub_f32_e32 v83, v154, v82
	v_exp_f32_e32 v84, v83
	v_mov_b32_e32 v83, v155
	v_mul_f32_e32 v80, v80, v84
	v_mov_b64_e32 v[84:85], v[82:83]
	s_cbranch_execnz .LBB0_248

; template <int MODE>
; __device__ __forceinline__ void nsa_compute(int cur, int buf, int t, int hl, u64 mymask, const bf16x8 (&Qf)[2][2], f32x4 (&O)[4][2], float (&m)[2], float (&l)[2],
;                                             const float (&inv)[2], float* impw, char* lds) {
;     ...
; #pragma unroll
;     for (int ks = 0; ks < 2; ++ks)
; #pragma unroll
;       for (int kk = 0; kk < 2; ++kk) kfr[ks][kk] = *(const bf16x8*)(kt + (32 * s2 + 16 * kk + fr) * 128 + (((ks * 4 + fq) ^ (fr & 7)) << 4));
;     __builtin_amdgcn_s_setprio(1);
; #pragma unroll
;     for (int ks = 0; ks < 2; ++ks)
; #pragma unroll
;       for (int kk = 0; kk < 2; ++kk)
; #pragma unroll
;         for (int r = 0; r < 2; ++r) S[kk][r] = mfma16(kfr[ks][kk], Qf[r][ks], S[kk][r]);
;     __builtin_amdgcn_s_setprio(0);
;     bf16x8 Pf[2];
;     float g1s[2] = {0.f, 0.f}, p3s[2] = {0.f, 0.f};
; #pragma unroll
;     for (int r = 0; r < 2; ++r) {
;       float sv[2][4];
; #pragma unroll
;       for (int kk = 0; kk < 2; ++kk)
; #pragma unroll
;         for (int e = 0; e < 4; ++e) {
;           const int off = 32 * s2 + 16 * kk + e;
;           int idx;
;           if (MODE <= 1) { idx = base - 16 * off; idx = idx > 0 ? idx : 0; } else idx = base - off;
;           sv[kk][e] = S[kk][r][e] * (0.125f * LOG2E) + tb[r * TS + idx];
;         }
;       float pv[2][4];
;       if (MODE == 1) {
; #pragma unroll
;         for (int kk = 0; kk < 2; ++kk)
; #pragma unroll
;           for (int e = 0; e < 4; ++e) pv[kk][e] = __builtin_amdgcn_exp2f(sv[kk][e] - m[r]) * inv[r];
; #pragma unroll
;         for (int kk = 0; kk < 2; ++kk) { g1s[kk] += pv[kk][0] + pv[kk][1] + pv[kk][2] + 0.5f * pv[kk][3]; p3s[kk] += 0.5f * pv[kk][3]; }
;       } else {
;         const float mxa = fmaxf(fmaxf(sv[0][0], sv[0][1]), sv[0][2]), mxb = fmaxf(fmaxf(sv[0][3], sv[1][0]), sv[1][1]);
;         float mx = fmaxf(fmaxf(fmaxf(sv[1][2], sv[1][3]), mxa), mxb);
;         if (MODE == 2) mx = selok ? mx : -__builtin_inff();
;         if (__any(mx > m[r] + 8.0f)) {
;           mx = fmaxf(mx, __shfl_xor(mx, 16)); mx = fmaxf(mx, __shfl_xor(mx, 32));
;           const float mn = fmaxf(m[r], mx), al = __builtin_amdgcn_exp2f(m[r] - mn);
;           m[r] = mn; l[r] *= al;
;           if (MODE != 0) {
; #pragma unroll
;             for (int df = 0; df < 4; ++df) O[df][r] *= al;
;           }
;         }
.LBB0_251:
	v_sub_f32_e32 v72, v100, v73
	v_exp_f32_e32 v72, v72
	v_sub_f32_e32 v74, v98, v73
	v_exp_f32_e32 v74, v74
	v_add_f32_e32 v72, 0, v72
	v_add_f32_e32 v72, v74, v72
	v_sub_f32_e32 v74, v96, v73
	v_exp_f32_e32 v74, v74
	s_nop 0
	v_add_f32_e32 v72, v74, v72
	v_sub_f32_e32 v74, v94, v73
	v_exp_f32_e32 v74, v74
	s_nop 0
	v_add_f32_e32 v72, v74, v72
	v_sub_f32_e32 v74, v92, v73
	v_exp_f32_e32 v74, v74
	s_nop 0
	v_add_f32_e32 v72, v74, v72
	v_sub_f32_e32 v74, v91, v73
	v_exp_f32_e32 v74, v74
	s_nop 0
	v_add_f32_e32 v72, v74, v72
	v_sub_f32_e32 v74, v90, v73
	v_exp_f32_e32 v74, v74
	v_sub_f32_e32 v73, v89, v73
	v_exp_f32_e32 v73, v73
	v_add_f32_e32 v72, v74, v72
	v_add_f32_e32 v72, v73, v72
	v_add_f32_e32 v81, v81, v72
	ds_read_b128 v[72:75], v87 offset:4096
	ds_read_b128 v[76:79], v87 offset:6144
	ds_read_b128 v[90:93], v88 offset:4096
	ds_read_b128 v[94:97], v88 offset:6144
	s_waitcnt lgkmcnt(3)
	v_mfma_f32_16x16x32_bf16 v[98:101], v[72:75], v[0:3], 0
	v_mfma_f32_16x16x32_bf16 v[72:75], v[72:75], v[8:11], 0
	s_waitcnt lgkmcnt(2)
	v_mfma_f32_16x16x32_bf16 v[102:105], v[76:79], v[0:3], 0
	v_mfma_f32_16x16x32_bf16 v[106:109], v[76:79], v[8:11], 0
	s_waitcnt lgkmcnt(1)
	v_mfma_f32_16x16x32_bf16 v[98:101], v[90:93], v[4:7], v[98:101]
	v_mfma_f32_16x16x32_bf16 v[76:79], v[90:93], v[12:15], v[72:75]
	s_waitcnt lgkmcnt(0)
	v_mfma_f32_16x16x32_bf16 v[102:105], v[94:97], v[4:7], v[102:105]
	v_mfma_f32_16x16x32_bf16 v[72:75], v[94:97], v[12:15], v[106:109]
	v_add_u32_e32 v84, 0xfffffe00, v86
	v_max_i32_e32 v84, 0, v84
	v_lshl_add_u32 v88, v84, 2, v181
	v_add_u32_e32 v84, 0xfffffdf0, v86
	v_max_i32_e32 v84, 0, v84
	v_lshl_add_u32 v89, v84, 2, v181
	ds_read_b32 v93, v88 offset:33792
	ds_read_b32 v95, v89 offset:33792
	v_add_u32_e32 v84, 0xfffffde0, v86
	v_max_i32_e32 v84, 0, v84
	v_lshl_add_u32 v90, v84, 2, v181
	v_add_u32_e32 v84, 0xfffffdd0, v86
	v_max_i32_e32 v84, 0, v84
	v_lshl_add_u32 v91, v84, 2, v181
	ds_read_b32 v97, v90 offset:33792
	s_waitcnt lgkmcnt(1)
	v_fmac_f32_e32 v95, 0x3e38aa3b, v99
	ds_read_b32 v99, v91 offset:33792
	v_add_u32_e32 v84, 0xfffffd00, v86
	v_max_i32_e32 v84, 0, v84
	v_lshl_add_u32 v92, v84, 2, v181
	v_add_u32_e32 v84, 0xfffffcf0, v86
	v_max_i32_e32 v84, 0, v84
	v_lshl_add_u32 v94, v84, 2, v181
	s_waitcnt lgkmcnt(1)
	v_fmac_f32_e32 v97, 0x3e38aa3b, v100
	ds_read_b32 v100, v92 offset:33792
	s_waitcnt lgkmcnt(1)
	v_fmac_f32_e32 v99, 0x3e38aa3b, v101
	ds_read_b32 v101, v94 offset:33792
	v_add_u32_e32 v84, 0xfffffce0, v86
	v_max_i32_e32 v84, 0, v84
	v_lshl_add_u32 v96, v84, 2, v181
	v_add_u32_e32 v84, 0xfffffcd0, v86
	v_max_i32_e32 v84, 0, v84
	v_fmac_f32_e32 v93, 0x3e38aa3b, v98
	v_lshl_add_u32 v98, v84, 2, v181
	s_waitcnt lgkmcnt(1)
	v_fmac_f32_e32 v100, 0x3e38aa3b, v102
	ds_read_b32 v102, v96 offset:33792
	s_waitcnt lgkmcnt(1)
	v_fmac_f32_e32 v101, 0x3e38aa3b, v103
	ds_read_b32 v103, v98 offset:33792
	v_max3_f32 v84, v93, v95, v97
	v_max3_f32 v85, v99, v100, v101
	s_waitcnt lgkmcnt(1)
	v_fmac_f32_e32 v102, 0x3e38aa3b, v104
	s_waitcnt lgkmcnt(0)
	v_fmac_f32_e32 v103, 0x3e38aa3b, v105
	v_max_f32_e32 v86, v102, v103
	v_max3_f32 v84, v86, v84, v85
	v_add_f32_e32 v85, 0x41000000, v82
	v_cmp_gt_f32_e32 vcc, v84, v85
	s_cbranch_vccz .LBB0_275
	v_cmp_lt_i32_e32 vcc, v220, v218
	v_mov_b32_e32 v87, v83
	s_nop 0
	v_cndmask_b32_e32 v85, v212, v220, vcc
	v_lshlrev_b32_e32 v85, 2, v85
	ds_bpermute_b32 v85, v85, v84
	v_cmp_lt_i32_e32 vcc, v219, v218
	v_max_f32_e32 v84, v84, v84
	s_waitcnt lgkmcnt(0)
	v_max_f32_e32 v85, v85, v85
	v_cndmask_b32_e32 v86, v212, v219, vcc
	v_max_f32_e32 v84, v84, v85
	v_lshlrev_b32_e32 v85, 2, v86
	ds_bpermute_b32 v85, v85, v84
	s_waitcnt lgkmcnt(0)
	v_max3_f32 v86, v82, v84, v85
	v_sub_f32_e32 v84, v82, v86
	v_exp_f32_e32 v84, v84
	s_nop 0
	v_mul_f32_e32 v80, v80, v84
	v_mov_b64_e32 v[84:85], v[86:87]
	s_cbranch_execnz .LBB0_254

; template <int MODE>
; __device__ __forceinline__ void nsa_compute(int cur, int buf, int t, int hl, u64 mymask, const bf16x8 (&Qf)[2][2], f32x4 (&O)[4][2], float (&m)[2], float (&l)[2],
;                                             const float (&inv)[2], float* impw, char* lds) {
;     ...
; #pragma unroll
;     for (int ks = 0; ks < 2; ++ks)
; #pragma unroll
;       for (int kk = 0; kk < 2; ++kk) kfr[ks][kk] = *(const bf16x8*)(kt + (32 * s2 + 16 * kk + fr) * 128 + (((ks * 4 + fq) ^ (fr & 7)) << 4));
;     __builtin_amdgcn_s_setprio(1);
; #pragma unroll
;     for (int ks = 0; ks < 2; ++ks)
; #pragma unroll
;       for (int kk = 0; kk < 2; ++kk)
; #pragma unroll
;         for (int r = 0; r < 2; ++r) S[kk][r] = mfma16(kfr[ks][kk], Qf[r][ks], S[kk][r]);
;     __builtin_amdgcn_s_setprio(0);
;     bf16x8 Pf[2];
;     float g1s[2] = {0.f, 0.f}, p3s[2] = {0.f, 0.f};
; #pragma unroll
;     for (int r = 0; r < 2; ++r) {
;       float sv[2][4];
; #pragma unroll
;       for (int kk = 0; kk < 2; ++kk)
; #pragma unroll
;         for (int e = 0; e < 4; ++e) {
;           const int off = 32 * s2 + 16 * kk + e;
;           int idx;
;           if (MODE <= 1) { idx = base - 16 * off; idx = idx > 0 ? idx : 0; } else idx = base - off;
;           sv[kk][e] = S[kk][r][e] * (0.125f * LOG2E) + tb[r * TS + idx];
;         }
;       float pv[2][4];
;       if (MODE == 1) {
; #pragma unroll
;         for (int kk = 0; kk < 2; ++kk)
; #pragma unroll
;           for (int e = 0; e < 4; ++e) pv[kk][e] = __builtin_amdgcn_exp2f(sv[kk][e] - m[r]) * inv[r];
; #pragma unroll
;         for (int kk = 0; kk < 2; ++kk) { g1s[kk] += pv[kk][0] + pv[kk][1] + pv[kk][2] + 0.5f * pv[kk][3]; p3s[kk] += 0.5f * pv[kk][3]; }
;       } else {
;         const float mxa = fmaxf(fmaxf(sv[0][0], sv[0][1]), sv[0][2]), mxb = fmaxf(fmaxf(sv[0][3], sv[1][0]), sv[1][1]);
;         float mx = fmaxf(fmaxf(fmaxf(sv[1][2], sv[1][3]), mxa), mxb);
;         if (MODE == 2) mx = selok ? mx : -__builtin_inff();
;         if (__any(mx > m[r] + 8.0f)) {
;           mx = fmaxf(mx, __shfl_xor(mx, 16)); mx = fmaxf(mx, __shfl_xor(mx, 32));
;           const float mn = fmaxf(m[r], mx), al = __builtin_amdgcn_exp2f(m[r] - mn);
;           m[r] = mn; l[r] *= al;
;           if (MODE != 0) {
; #pragma unroll
;             for (int df = 0; df < 4; ++df) O[df][r] *= al;
;           }
;         }
.LBB0_290:
	v_mov_b32 v72, v179
	s_lshl_b32 s71, s68, 13
	v_lshrrev_b32_e32 v73, 4, v72
	v_bfe_u32 v111, v72, 4, 2
	v_and_b32_e32 v80, 7, v72
	v_and_b32_e32 v110, 15, v72
	v_bitop3_b32 v72, v73, v80, 3 bitop3:0x6c
	v_bitop3_b32 v80, v111, v80, 4 bitop3:0x36
	v_lshlrev_b32_e32 v85, 7, v110
	v_lshl_or_b32 v86, v72, 4, s71
	v_lshl_or_b32 v87, v80, 4, s71
	v_or_b32_e32 v76, v86, v85
	v_or_b32_e32 v88, v87, v85
	ds_read_b128 v[72:75], v76
	ds_read_b128 v[76:79], v76 offset:2048
	ds_read_b128 v[80:83], v88
	ds_read_b128 v[88:91], v88 offset:2048
	s_mov_b32 s17, s69
	v_lshlrev_b32_e32 v84, 6, v111
	s_mov_b32 s69, s16
	s_lshl_b32 s16, s68, 9
	v_lshl_or_b32 v84, s17, 10, v84
	s_add_i32 s70, s71, s16
	v_sub_u32_e32 v84, v183, v84
	v_lshl_or_b32 v116, s17, 4, v111
	v_mul_u32_u24_e32 v117, 0x41, v110
	s_waitcnt lgkmcnt(3)
	v_mfma_f32_16x16x32_bf16 v[92:95], v[72:75], v[0:3], 0
	v_mfma_f32_16x16x32_bf16 v[72:75], v[72:75], v[8:11], 0
	s_waitcnt lgkmcnt(2)
	v_mfma_f32_16x16x32_bf16 v[96:99], v[76:79], v[0:3], 0
	v_mfma_f32_16x16x32_bf16 v[76:79], v[76:79], v[8:11], 0
	s_waitcnt lgkmcnt(1)
	v_mfma_f32_16x16x32_bf16 v[92:95], v[80:83], v[4:7], v[92:95]
	s_waitcnt vmcnt(0)
	v_mfma_f32_16x16x32_bf16 v[80:83], v[80:83], v[12:15], v[72:75]
	s_waitcnt lgkmcnt(0)
	v_mfma_f32_16x16x32_bf16 v[72:75], v[88:91], v[4:7], v[96:99]
	v_mfma_f32_16x16x32_bf16 v[88:91], v[88:91], v[12:15], v[76:79]
	s_nop 1
	s_nop 0
	v_max_i32_e32 v76, 0, v84
	v_lshl_add_u32 v76, v76, 2, v181
	ds_read2st64_b32 v[78:79], v76 offset0:132 offset1:197
	v_add_u32_e32 v77, -16, v84
	v_max_i32_e32 v77, 0, v77
	v_lshl_add_u32 v77, v77, 2, v181
	ds_read2st64_b32 v[96:97], v77 offset0:132 offset1:197
	s_waitcnt lgkmcnt(1)
	v_fmamk_f32 v76, v92, 0x3e38aa3b, v78
	v_subrev_u32_e32 v92, 48, v84
	v_max_i32_e32 v92, 0, v92
	v_lshl_add_u32 v92, v92, 2, v181
	v_subrev_u32_e32 v78, 32, v84
	ds_read2st64_b32 v[100:101], v92 offset0:132 offset1:197
	v_add_u32_e32 v92, 0xffffff00, v84
	v_max_i32_e32 v78, 0, v78
	v_max_i32_e32 v92, 0, v92
	v_lshl_add_u32 v78, v78, 2, v181
	v_lshl_add_u32 v92, v92, 2, v181
	ds_read2st64_b32 v[98:99], v78 offset0:132 offset1:197
	ds_read2st64_b32 v[102:103], v92 offset0:132 offset1:197
	s_waitcnt lgkmcnt(3)
	v_fmamk_f32 v77, v93, 0x3e38aa3b, v96
	v_fmac_f32_e32 v79, 0x3e38aa3b, v80
	v_fmac_f32_e32 v97, 0x3e38aa3b, v81
	s_waitcnt lgkmcnt(1)
	v_fmamk_f32 v78, v94, 0x3e38aa3b, v98
	v_fmamk_f32 v94, v95, 0x3e38aa3b, v100
	s_waitcnt lgkmcnt(0)
	v_fmamk_f32 v95, v72, 0x3e38aa3b, v102
	v_add_u32_e32 v72, 0xfffffef0, v84
	v_max_i32_e32 v72, 0, v72
	v_lshl_add_u32 v72, v72, 2, v181
	ds_read2st64_b32 v[104:105], v72 offset0:132 offset1:197
	v_add_u32_e32 v72, 0xfffffee0, v84
	v_max_i32_e32 v72, 0, v72
	v_lshl_add_u32 v72, v72, 2, v181
	ds_read2st64_b32 v[106:107], v72 offset0:132 offset1:197
	v_add_u32_e32 v72, 0xfffffed0, v84
	v_max_i32_e32 v72, 0, v72
	v_lshl_add_u32 v72, v72, 2, v181
	s_waitcnt lgkmcnt(1)
	v_fmamk_f32 v96, v73, 0x3e38aa3b, v104
	ds_read2st64_b32 v[108:109], v72 offset0:132 offset1:197
	v_sub_f32_e32 v72, v76, v154
	v_sub_f32_e32 v73, v77, v154
	v_exp_f32_e32 v72, v72
	v_exp_f32_e32 v73, v73
	s_waitcnt lgkmcnt(0)
	v_fmamk_f32 v100, v75, 0x3e38aa3b, v108
	v_sub_f32_e32 v75, v96, v154
	v_fmac_f32_e32 v99, 0x3e38aa3b, v82
	v_pk_mul_f32 v[92:93], v[156:157], v[72:73]
	v_sub_f32_e32 v72, v78, v154
	v_sub_f32_e32 v73, v94, v154
	v_exp_f32_e32 v72, v72
	v_exp_f32_e32 v73, v73
	v_add_f32_e32 v78, v92, v93
	v_cvt_pk_bf16_f32 v92, v92, v93
	v_fmac_f32_e32 v101, 0x3e38aa3b, v83
	v_pk_mul_f32 v[72:73], v[156:157], v[72:73]
	v_fmac_f32_e32 v103, 0x3e38aa3b, v88
	v_add_f32_e32 v78, v72, v78
	v_fmac_f32_e32 v78, 0.5, v73
	v_cvt_pk_bf16_f32 v93, v72, v73
	v_sub_f32_e32 v72, v79, v155
	v_add_f32_e32 v96, 0, v78
	v_exp_f32_e32 v78, v72
	v_sub_f32_e32 v72, v97, v155
	v_exp_f32_e32 v79, v72
	v_sub_f32_e32 v72, v99, v155
	v_fmac_f32_e32 v105, 0x3e38aa3b, v89
	v_fmac_f32_e32 v107, 0x3e38aa3b, v90
	v_pk_mul_f32 v[88:89], v[158:159], v[78:79]
	v_exp_f32_e32 v78, v72
	v_sub_f32_e32 v72, v101, v155
	v_exp_f32_e32 v79, v72
	v_sub_f32_e32 v72, v103, v155
	v_fmac_f32_e32 v109, 0x3e38aa3b, v91
	v_fmamk_f32 v98, v74, 0x3e38aa3b, v106
	v_pk_mul_f32 v[80:81], v[158:159], v[78:79]
	v_exp_f32_e32 v78, v72
	v_sub_f32_e32 v72, v105, v155
	v_exp_f32_e32 v79, v72
	v_sub_f32_e32 v72, v107, v155
	v_exp_f32_e32 v82, v72
	v_sub_f32_e32 v72, v109, v155
	v_exp_f32_e32 v83, v72
	v_add_f32_e32 v72, v88, v89
	v_add_f32_e32 v72, v80, v72
	v_fmac_f32_e32 v72, 0.5, v81
	v_add_f32_e32 v90, v96, v72
	v_mul_u32_u24_e32 v72, 0x44, v110
	v_cvt_pk_bf16_f32 v97, v80, v81
	v_lshlrev_b32_e32 v72, 1, v72
	v_lshlrev_b32_e32 v80, 3, v111
	v_sub_f32_e32 v74, v95, v154
	v_sub_f32_e32 v76, v98, v154
	v_sub_f32_e32 v77, v100, v154
	v_cvt_pk_bf16_f32 v96, v88, v89
	v_add3_u32 v89, s70, v72, v80
	v_exp_f32_e32 v74, v74
	v_exp_f32_e32 v75, v75
	v_exp_f32_e32 v76, v76
	v_exp_f32_e32 v77, v77
	v_add_u32_e32 v72, 0x4000, v89
	v_add_u32_e32 v80, 0x4800, v89
	v_add_u32_e32 v88, 0x5000, v89
	v_add_u32_e32 v89, 0x5800, v89
	ds_read2_b64 v[100:103], v72 offset1:4
	ds_read2_b64 v[104:107], v80 offset0:16 offset1:20
	ds_read2_b64 v[108:111], v88 offset0:32 offset1:36
	ds_read2_b64 v[112:115], v89 offset0:48 offset1:52
	v_pk_mul_f32 v[74:75], v[156:157], v[74:75]
	v_pk_mul_f32 v[76:77], v[156:157], v[76:77]
	v_pk_mul_f32 v[78:79], v[158:159], v[78:79]
	v_pk_mul_f32 v[82:83], v[158:159], v[82:83]
	v_cvt_pk_bf16_f32 v94, v74, v75
	v_cvt_pk_bf16_f32 v95, v76, v77
	v_cvt_pk_bf16_f32 v98, v78, v79
	v_cvt_pk_bf16_f32 v99, v82, v83
	s_waitcnt lgkmcnt(3)
	v_mfma_f32_16x16x32_bf16 v[44:47], v[100:103], v[92:95], v[44:47]
	v_mfma_f32_16x16x32_bf16 v[28:31], v[100:103], v[96:99], v[28:31]
	s_waitcnt lgkmcnt(2)
; __device__ __forceinline__ f32x4 mfma16(bf16x8 a, bf16x8 b, f32x4 c) { return __builtin_amdgcn_mfma_f32_16x16x32_bf16(a, b, c, 0, 0, 0); }
; template <int MODE>
; __device__ __forceinline__ void nsa_compute(int cur, int buf, int t, int hl, u64 mymask, const bf16x8 (&Qf)[2][2], f32x4 (&O)[4][2], float (&m)[2], float (&l)[2],
;                                             const float (&inv)[2], float* impw, char* lds) {
;     ...
; #pragma unroll
;     for (int ks = 0; ks < 2; ++ks)
; #pragma unroll
;       for (int kk = 0; kk < 2; ++kk) kfr[ks][kk] = *(const bf16x8*)(kt + (32 * s2 + 16 * kk + fr) * 128 + (((ks * 4 + fq) ^ (fr & 7)) << 4));
;     __builtin_amdgcn_s_setprio(1);
; #pragma unroll
;     for (int ks = 0; ks < 2; ++ks)
; #pragma unroll
;       for (int kk = 0; kk < 2; ++kk)
; #pragma unroll
;         for (int r = 0; r < 2; ++r) S[kk][r] = mfma16(kfr[ks][kk], Qf[r][ks], S[kk][r]);
;     __builtin_amdgcn_s_setprio(0);
;     bf16x8 Pf[2];
;     float g1s[2] = {0.f, 0.f}, p3s[2] = {0.f, 0.f};
; #pragma unroll
;     for (int r = 0; r < 2; ++r) {
;       float sv[2][4];
; #pragma unroll
;       for (int kk = 0; kk < 2; ++kk)
; #pragma unroll
;         for (int e = 0; e < 4; ++e) {
;           const int off = 32 * s2 + 16 * kk + e;
;           int idx;
;           if (MODE <= 1) { idx = base - 16 * off; idx = idx > 0 ? idx : 0; } else idx = base - off;
;           sv[kk][e] = S[kk][r][e] * (0.125f * LOG2E) + tb[r * TS + idx];
;         }
;       float pv[2][4];
;       if (MODE == 1) {
; #pragma unroll
;         for (int kk = 0; kk < 2; ++kk)
; #pragma unroll
;           for (int e = 0; e < 4; ++e) pv[kk][e] = __builtin_amdgcn_exp2f(sv[kk][e] - m[r]) * inv[r];
; #pragma unroll
;         for (int kk = 0; kk < 2; ++kk) { g1s[kk] += pv[kk][0] + pv[kk][1] + pv[kk][2] + 0.5f * pv[kk][3]; p3s[kk] += 0.5f * pv[kk][3]; }
;     ...
;       __builtin_amdgcn_s_setprio(1);
; #pragma unroll
;       for (int df = 0; df < 4; ++df)
; #pragma unroll
;         for (int r = 0; r < 2; ++r) O[df][r] = mfma16(vfr[df], Pf[r], O[df][r]);
;       __builtin_amdgcn_s_setprio(0);
;     }
;     if (MODE == 1) {
; #pragma unroll
;       for (int kk = 0; kk < 2; ++kk) {
;         const int j = cur * 16 + (2 * s2 + kk) * 4 + fq;
;         atomicAdd(&impw[fr * 65 + j], g1s[kk]);
;         if (j + 1 < 64) atomicAdd(&impw[fr * 65 + j + 1], p3s[kk]);
;       }
;     }
	v_mfma_f32_16x16x32_bf16 v[40:43], v[104:107], v[92:95], v[40:43]
	v_mfma_f32_16x16x32_bf16 v[24:27], v[104:107], v[96:99], v[24:27]
	s_waitcnt lgkmcnt(1)
	v_mfma_f32_16x16x32_bf16 v[36:39], v[108:111], v[92:95], v[36:39]
	v_mfma_f32_16x16x32_bf16 v[20:23], v[108:111], v[96:99], v[20:23]
	s_waitcnt lgkmcnt(0)
	v_mfma_f32_16x16x32_bf16 v[32:35], v[112:115], v[92:95], v[32:35]
	v_mfma_f32_16x16x32_bf16 v[16:19], v[112:115], v[96:99], v[16:19]
	v_lshlrev_b32_e32 v91, 2, v116
	v_lshlrev_b32_e32 v92, 2, v117
	v_add3_u32 v117, v184, v91, v92
	ds_add_f32 v117, v90
	v_cmp_gt_u32_e32 vcc, 63, v116
	s_and_saveexec_b64 s[16:17], vcc
	v_mul_f32_e32 v73, 0.5, v73
	v_mul_f32_e32 v81, 0.5, v81
	v_add_f32_e32 v73, 0, v73
	v_add_f32_e32 v73, v73, v81
	ds_add_f32 v117, v73 offset:4
	s_or_b64 exec, exec, s[16:17]
	v_add_f32_e32 v73, v74, v75
	v_add_f32_e32 v73, v76, v73
	v_add_f32_e32 v74, v78, v79
	v_fmac_f32_e32 v73, 0.5, v77
	v_add_f32_e32 v74, v82, v74
	v_add_f32_e32 v73, 0, v73
	v_fmac_f32_e32 v74, 0.5, v83
	v_add_f32_e32 v73, v73, v74
	ds_add_f32 v117, v73 offset:16
	v_or_b32_e32 v73, 4, v116
	v_cmp_gt_u32_e32 vcc, 63, v73
	s_and_saveexec_b64 s[16:17], vcc
	v_mul_f32_e32 v73, 0.5, v77
	v_mul_f32_e32 v74, 0.5, v83
	v_add_f32_e32 v73, 0, v73
	v_add_f32_e32 v73, v73, v74
	ds_add_f32 v117, v73 offset:20
	s_or_b64 exec, exec, s[16:17]
	v_add_u32_e32 v73, v86, v85
	ds_read_b128 v[74:77], v73 offset:4096
	ds_read_b128 v[90:93], v73 offset:6144
	v_add_u32_e32 v73, v87, v85
	ds_read_b128 v[94:97], v73 offset:4096
	ds_read_b128 v[98:101], v73 offset:6144
	s_waitcnt lgkmcnt(3)
	v_mfma_f32_16x16x32_bf16 v[102:105], v[74:77], v[0:3], 0
	v_mfma_f32_16x16x32_bf16 v[74:77], v[74:77], v[8:11], 0
	s_waitcnt lgkmcnt(2)
	v_mfma_f32_16x16x32_bf16 v[106:109], v[90:93], v[0:3], 0
	v_mfma_f32_16x16x32_bf16 v[90:93], v[90:93], v[8:11], 0
	s_waitcnt lgkmcnt(1)
	v_mfma_f32_16x16x32_bf16 v[102:105], v[94:97], v[4:7], v[102:105]
	v_mfma_f32_16x16x32_bf16 v[74:77], v[94:97], v[12:15], v[74:77]
	s_waitcnt lgkmcnt(0)
	v_mfma_f32_16x16x32_bf16 v[94:97], v[98:101], v[4:7], v[106:109]
	v_mfma_f32_16x16x32_bf16 v[90:93], v[98:101], v[12:15], v[90:93]
	v_add_u32_e32 v73, 0xfffffe00, v84
	v_max_i32_e32 v73, 0, v73
	v_lshl_add_u32 v73, v73, 2, v181
	ds_read2st64_b32 v[78:79], v73 offset0:132 offset1:197
	v_add_u32_e32 v81, 0xfffffde0, v84
	v_add_u32_e32 v85, 0xfffffd00, v84
	v_max_i32_e32 v81, 0, v81
	v_max_i32_e32 v85, 0, v85
	s_waitcnt lgkmcnt(0)
	v_fmamk_f32 v73, v102, 0x3e38aa3b, v78
	v_add_u32_e32 v78, 0xfffffdf0, v84
	v_max_i32_e32 v78, 0, v78
	v_lshl_add_u32 v78, v78, 2, v181
	ds_read2st64_b32 v[82:83], v78 offset0:132 offset1:197
	v_lshl_add_u32 v81, v81, 2, v181
	v_lshl_add_u32 v85, v85, 2, v181
	ds_read2st64_b32 v[86:87], v81 offset0:132 offset1:197
	ds_read2st64_b32 v[100:101], v85 offset0:132 offset1:197
	s_waitcnt lgkmcnt(2)
	v_fmamk_f32 v78, v103, 0x3e38aa3b, v82
	v_add_u32_e32 v82, 0xfffffdd0, v84
	v_max_i32_e32 v82, 0, v82
	v_lshl_add_u32 v82, v82, 2, v181
	ds_read2st64_b32 v[98:99], v82 offset0:132 offset1:197
	v_add_u32_e32 v85, 0xfffffcf0, v84
	v_max_i32_e32 v85, 0, v85
	v_lshl_add_u32 v85, v85, 2, v181
	ds_read2st64_b32 v[102:103], v85 offset0:132 offset1:197
	v_add_u32_e32 v85, 0xfffffce0, v84
	s_waitcnt lgkmcnt(3)
	v_fmac_f32_e32 v87, 0x3e38aa3b, v76
	s_waitcnt lgkmcnt(1)
	v_fmac_f32_e32 v99, 0x3e38aa3b, v77
	v_max_i32_e32 v85, 0, v85
	v_add_u32_e32 v84, 0xfffffcd0, v84
	v_sub_f32_e32 v76, v87, v155
	v_sub_f32_e32 v77, v99, v155
	v_lshl_add_u32 v85, v85, 2, v181
	v_max_i32_e32 v84, 0, v84
	v_exp_f32_e32 v76, v76
	v_exp_f32_e32 v77, v77
	v_fmamk_f32 v81, v104, 0x3e38aa3b, v86
	v_fmamk_f32 v82, v105, 0x3e38aa3b, v98
	v_fmamk_f32 v86, v94, 0x3e38aa3b, v100
	s_waitcnt lgkmcnt(0)
	v_fmamk_f32 v98, v95, 0x3e38aa3b, v102
	ds_read2st64_b32 v[94:95], v85 offset0:132 offset1:197
	v_lshl_add_u32 v84, v84, 2, v181
	ds_read2st64_b32 v[84:85], v84 offset0:132 offset1:197
	v_fmac_f32_e32 v101, 0x3e38aa3b, v90
	v_fmac_f32_e32 v103, 0x3e38aa3b, v91
	v_pk_mul_f32 v[112:113], v[158:159], v[76:77]
	v_sub_f32_e32 v76, v101, v155
	v_sub_f32_e32 v77, v103, v155
	v_sub_f32_e32 v73, v73, v154
	v_exp_f32_e32 v76, v76
	v_exp_f32_e32 v77, v77
	s_waitcnt lgkmcnt(1)
; template <int MODE>
; __device__ __forceinline__ void nsa_compute(int cur, int buf, int t, int hl, u64 mymask, const bf16x8 (&Qf)[2][2], f32x4 (&O)[4][2], float (&m)[2], float (&l)[2],
;                                             const float (&inv)[2], float* impw, char* lds) {
;     ...
;       float pv[2][4];
;       if (MODE == 1) {
; #pragma unroll
;         for (int kk = 0; kk < 2; ++kk)
; #pragma unroll
;           for (int e = 0; e < 4; ++e) pv[kk][e] = __builtin_amdgcn_exp2f(sv[kk][e] - m[r]) * inv[r];
; #pragma unroll
;         for (int kk = 0; kk < 2; ++kk) { g1s[kk] += pv[kk][0] + pv[kk][1] + pv[kk][2] + 0.5f * pv[kk][3]; p3s[kk] += 0.5f * pv[kk][3]; }
;       } else {
;         const float mxa = fmaxf(fmaxf(sv[0][0], sv[0][1]), sv[0][2]), mxb = fmaxf(fmaxf(sv[0][3], sv[1][0]), sv[1][1]);
;         float mx = fmaxf(fmaxf(fmaxf(sv[1][2], sv[1][3]), mxa), mxb);
;         if (MODE == 2) mx = selok ? mx : -__builtin_inff();
;         if (__any(mx > m[r] + 8.0f)) {
;           mx = fmaxf(mx, __shfl_xor(mx, 16)); mx = fmaxf(mx, __shfl_xor(mx, 32));
;           const float mn = fmaxf(m[r], mx), al = __builtin_amdgcn_exp2f(m[r] - mn);
;           m[r] = mn; l[r] *= al;
;           if (MODE != 0) {
; #pragma unroll
;             for (int df = 0; df < 4; ++df) O[df][r] *= al;
;           }
;         }
;         const float me = (MODE == 2) ? (selok ? m[r] : __builtin_inff()) : m[r];
;         float ps = 0.f;
; #pragma unroll
;         for (int kk = 0; kk < 2; ++kk)
; #pragma unroll
;           for (int e = 0; e < 4; ++e) { pv[kk][e] = __builtin_amdgcn_exp2f(sv[kk][e] - me); ps += pv[kk][e]; }
;         l[r] += ps;
;       }
;       if (MODE != 0) {
;         const unsigned w0 = pk2(pv[0][0], pv[0][1]), w1 = pk2(pv[0][2], pv[0][3]), w2 = pk2(pv[1][0], pv[1][1]), w3 = pk2(pv[1][2], pv[1][3]);
;         u32x4 pw; pw.x = w0; pw.y = w1; pw.z = w2; pw.w = w3;
;         Pf[r] = __builtin_bit_cast(bf16x8, pw);
;       }
;     }
;     if (MODE != 0) {
;       bf16x8 vfr[4];
; #pragma unroll
;       for (int df = 0; df < 4; ++df) {
;         const bf16x4 va = *(const bf16x4*)(vt + (df * 16 + fr) * 68 + 32 * s2 + 4 * fq);
;         const bf16x4 vb = *(const bf16x4*)(vt + (df * 16 + fr) * 68 + 32 * s2 + 16 + 4 * fq);
;         bf16x8 vf; vf[0] = va[0]; vf[1] = va[1]; vf[2] = va[2]; vf[3] = va[3]; vf[4] = vb[0]; vf[5] = vb[1]; vf[6] = vb[2]; vf[7] = vb[3];
	v_fmamk_f32 v94, v96, 0x3e38aa3b, v94
	v_exp_f32_e32 v96, v73
	v_sub_f32_e32 v73, v78, v154
	s_waitcnt lgkmcnt(0)
	v_fmamk_f32 v84, v97, 0x3e38aa3b, v84
	v_exp_f32_e32 v97, v73
	v_sub_f32_e32 v73, v81, v154
	v_fmac_f32_e32 v79, 0x3e38aa3b, v74
	v_fmac_f32_e32 v83, 0x3e38aa3b, v75
	v_exp_f32_e32 v104, v73
	v_sub_f32_e32 v73, v82, v154
	v_fmac_f32_e32 v95, 0x3e38aa3b, v92
	v_fmac_f32_e32 v85, 0x3e38aa3b, v93
	v_sub_f32_e32 v74, v79, v155
	v_sub_f32_e32 v75, v83, v155
	v_exp_f32_e32 v105, v73
	v_sub_f32_e32 v73, v86, v154
	v_exp_f32_e32 v74, v74
	v_exp_f32_e32 v75, v75
	v_pk_mul_f32 v[110:111], v[158:159], v[76:77]
	v_sub_f32_e32 v76, v95, v155
	v_sub_f32_e32 v77, v85, v155
	v_exp_f32_e32 v106, v73
	v_sub_f32_e32 v73, v98, v154
	v_exp_f32_e32 v76, v76
	v_exp_f32_e32 v77, v77
	v_exp_f32_e32 v107, v73
	v_sub_f32_e32 v73, v94, v154
	v_pk_mul_f32 v[96:97], v[156:157], v[96:97]
	v_exp_f32_e32 v108, v73
	v_sub_f32_e32 v73, v84, v154
	v_pk_mul_f32 v[104:105], v[156:157], v[104:105]
	v_exp_f32_e32 v109, v73
	v_add_f32_e32 v73, v96, v97
	v_pk_mul_f32 v[74:75], v[158:159], v[74:75]
	v_add_f32_e32 v73, v104, v73
	v_pk_mul_f32 v[114:115], v[158:159], v[76:77]
	v_add_f32_e32 v76, v74, v75
	v_fmac_f32_e32 v73, 0.5, v105
	v_add_f32_e32 v76, v112, v76
	v_add_f32_e32 v73, 0, v73
	v_fmac_f32_e32 v76, 0.5, v113
	v_cvt_pk_bf16_f32 v119, v104, v105
	v_add_f32_e32 v104, v73, v76
	v_cvt_pk_bf16_f32 v122, v74, v75
	ds_read2_b64 v[72:75], v72 offset0:8 offset1:12
	ds_read2_b64 v[76:79], v80 offset0:24 offset1:28
	ds_read2_b64 v[80:83], v88 offset0:40 offset1:44
	ds_read2_b64 v[126:129], v89 offset0:56 offset1:60
	v_pk_mul_f32 v[106:107], v[156:157], v[106:107]
	v_pk_mul_f32 v[108:109], v[156:157], v[108:109]
	v_cvt_pk_bf16_f32 v118, v96, v97
	v_cvt_pk_bf16_f32 v120, v106, v107
	v_cvt_pk_bf16_f32 v121, v108, v109
	v_cvt_pk_bf16_f32 v123, v112, v113
	v_cvt_pk_bf16_f32 v124, v110, v111
	v_cvt_pk_bf16_f32 v125, v114, v115
	s_waitcnt lgkmcnt(3)
	v_mfma_f32_16x16x32_bf16 v[88:91], v[72:75], v[118:121], v[44:47]
	v_mfma_f32_16x16x32_bf16 v[96:99], v[72:75], v[122:125], v[28:31]
	s_waitcnt lgkmcnt(2)
	v_mfma_f32_16x16x32_bf16 v[100:103], v[76:79], v[118:121], v[40:43]
	v_mfma_f32_16x16x32_bf16 v[84:87], v[76:79], v[122:125], v[24:27]
	s_waitcnt lgkmcnt(1)
	v_mfma_f32_16x16x32_bf16 v[92:95], v[80:83], v[118:121], v[36:39]
	v_mfma_f32_16x16x32_bf16 v[76:79], v[80:83], v[122:125], v[20:23]
	s_waitcnt lgkmcnt(0)
	v_mfma_f32_16x16x32_bf16 v[80:83], v[126:129], v[118:121], v[32:35]
	v_mfma_f32_16x16x32_bf16 v[72:75], v[126:129], v[122:125], v[16:19]
	ds_add_f32 v117, v104 offset:32
	s_nop 0
	s_nop 0
	v_or_b32_e32 v16, 8, v116
	v_cmp_gt_u32_e32 vcc, 63, v16
	s_and_saveexec_b64 s[16:17], vcc
	v_mul_f32_e32 v16, 0.5, v105
	v_mul_f32_e32 v17, 0.5, v113
	v_add_f32_e32 v16, 0, v16
	v_add_f32_e32 v16, v16, v17
	ds_add_f32 v117, v16 offset:36
	s_or_b64 exec, exec, s[16:17]
	v_add_f32_e32 v16, v106, v107
	v_add_f32_e32 v16, v108, v16
	v_add_f32_e32 v17, v110, v111
	v_fmac_f32_e32 v16, 0.5, v109
	v_add_f32_e32 v17, v114, v17
	v_add_f32_e32 v16, 0, v16
	v_fmac_f32_e32 v17, 0.5, v115
	v_add_f32_e32 v16, v16, v17
	ds_add_f32 v117, v16 offset:48
	v_or_b32_e32 v16, 12, v116
	v_cmp_gt_u32_e32 vcc, 63, v16
	s_and_saveexec_b64 s[16:17], vcc
	v_mul_f32_e32 v16, 0.5, v109
	v_mul_f32_e32 v17, 0.5, v115
	v_add_f32_e32 v16, 0, v16
	v_add_f32_e32 v16, v16, v17
	ds_add_f32 v117, v16 offset:52
	s_or_b64 exec, exec, s[16:17]
	s_xor_b32 s68, s68, 1
	s_cmp_lt_i32 s67, 0
	s_cbranch_scc1 .LBB0_300
	v_mov_b32 v16, v179
	s_lshl_b32 s16, s68, 13
	v_ashrrev_i32_e32 v17, 3, v16
	v_xor_b32_e32 v19, v17, v16
	v_lshl_add_u32 v18, v17, 7, s16
	v_lshlrev_b32_e32 v19, 4, v19
	s_movk_i32 s17, 0x70
	v_lshlrev_b32_e32 v16, 3, v16
	v_and_or_b32 v18, v19, s17, v18
	s_lshl_b32 s17, s68, 9
	v_and_b32_e32 v16, 56, v16
	s_add_i32 s16, s16, s17
	v_mul_u32_u24_e32 v16, 0x88, v16
	v_lshlrev_b32_e32 v17, 1, v17
	v_add3_u32 v16, s16, v16, v17
	ds_write_b128 v18, v[56:59]
	ds_write_b16 v16, v60 offset:16384
	ds_write_b16_d16_hi v16, v60 offset:16520
	ds_write_b16 v16, v61 offset:16656
	ds_write_b16_d16_hi v16, v61 offset:16792
	ds_write_b16 v16, v62 offset:16928
	ds_write_b16_d16_hi v16, v62 offset:17064
	ds_write_b16 v16, v63 offset:17200
	ds_write_b16_d16_hi v16, v63 offset:17336

; template <int MODE>
; __device__ __forceinline__ void nsa_compute(int cur, int buf, int t, int hl, u64 mymask, const bf16x8 (&Qf)[2][2], f32x4 (&O)[4][2], float (&m)[2], float (&l)[2],
;                                             const float (&inv)[2], float* impw, char* lds) {
;     ...
; #pragma unroll
;     for (int ks = 0; ks < 2; ++ks)
; #pragma unroll
;       for (int kk = 0; kk < 2; ++kk) kfr[ks][kk] = *(const bf16x8*)(kt + (32 * s2 + 16 * kk + fr) * 128 + (((ks * 4 + fq) ^ (fr & 7)) << 4));
;     __builtin_amdgcn_s_setprio(1);
; #pragma unroll
;     for (int ks = 0; ks < 2; ++ks)
; #pragma unroll
;       for (int kk = 0; kk < 2; ++kk)
; #pragma unroll
;         for (int r = 0; r < 2; ++r) S[kk][r] = mfma16(kfr[ks][kk], Qf[r][ks], S[kk][r]);
;     __builtin_amdgcn_s_setprio(0);
;     bf16x8 Pf[2];
;     float g1s[2] = {0.f, 0.f}, p3s[2] = {0.f, 0.f};
; #pragma unroll
;     for (int r = 0; r < 2; ++r) {
;       float sv[2][4];
; #pragma unroll
;       for (int kk = 0; kk < 2; ++kk)
; #pragma unroll
;         for (int e = 0; e < 4; ++e) {
;           const int off = 32 * s2 + 16 * kk + e;
;           int idx;
;           if (MODE <= 1) { idx = base - 16 * off; idx = idx > 0 ? idx : 0; } else idx = base - off;
;           sv[kk][e] = S[kk][r][e] * (0.125f * LOG2E) + tb[r * TS + idx];
;         }
;       float pv[2][4];
;       if (MODE == 1) {
; #pragma unroll
;         for (int kk = 0; kk < 2; ++kk)
; #pragma unroll
;           for (int e = 0; e < 4; ++e) pv[kk][e] = __builtin_amdgcn_exp2f(sv[kk][e] - m[r]) * inv[r];
; #pragma unroll
;         for (int kk = 0; kk < 2; ++kk) { g1s[kk] += pv[kk][0] + pv[kk][1] + pv[kk][2] + 0.5f * pv[kk][3]; p3s[kk] += 0.5f * pv[kk][3]; }
;       } else {
;         const float mxa = fmaxf(fmaxf(sv[0][0], sv[0][1]), sv[0][2]), mxb = fmaxf(fmaxf(sv[0][3], sv[1][0]), sv[1][1]);
;         float mx = fmaxf(fmaxf(fmaxf(sv[1][2], sv[1][3]), mxa), mxb);
;         if (MODE == 2) mx = selok ? mx : -__builtin_inff();
;         if (__any(mx > m[r] + 8.0f)) {
;           mx = fmaxf(mx, __shfl_xor(mx, 16)); mx = fmaxf(mx, __shfl_xor(mx, 32));
;           const float mn = fmaxf(m[r], mx), al = __builtin_amdgcn_exp2f(m[r] - mn);
;           m[r] = mn; l[r] *= al;
;           if (MODE != 0) {
; #pragma unroll
;             for (int df = 0; df < 4; ++df) O[df][r] *= al;
;           }
;         }
.LBB0_302:
	s_cmp_lt_i32 s67, 0
	s_cbranch_scc1 .LBB0_330
	v_mov_b32 v16, v179
	s_lshl_b32 s73, s68, 13
	v_lshrrev_b32_e32 v17, 4, v16
	v_bfe_u32 v121, v16, 4, 2
	v_and_b32_e32 v24, 7, v16
	v_and_b32_e32 v120, 15, v16
	v_bitop3_b32 v16, v17, v24, 3 bitop3:0x6c
	v_bitop3_b32 v24, v121, v24, 4 bitop3:0x36
	v_lshlrev_b32_e32 v117, 7, v120
	v_lshl_or_b32 v118, v16, 4, s73
	v_lshl_or_b32 v119, v24, 4, s73
	v_or_b32_e32 v20, v118, v117
	v_or_b32_e32 v28, v119, v117
	ds_read_b128 v[16:19], v20
	ds_read_b128 v[20:23], v20 offset:2048
	ds_read_b128 v[24:27], v28
	ds_read_b128 v[28:31], v28 offset:2048
	v_lshlrev_b32_e32 v32, 6, v121
	s_lshl_b32 s16, s68, 9
	v_lshl_or_b32 v32, s67, 10, v32
	s_add_i32 s72, s73, s16
	v_sub_u32_e32 v116, v183, v32
	v_lshl_or_b32 v160, s67, 4, v121
	v_mul_u32_u24_e32 v126, 0x41, v120
	s_waitcnt lgkmcnt(3)
	v_mfma_f32_16x16x32_bf16 v[32:35], v[16:19], v[0:3], 0
	v_mfma_f32_16x16x32_bf16 v[16:19], v[16:19], v[8:11], 0
	s_waitcnt lgkmcnt(2)
	v_mfma_f32_16x16x32_bf16 v[36:39], v[20:23], v[0:3], 0
	v_mfma_f32_16x16x32_bf16 v[20:23], v[20:23], v[8:11], 0
	s_waitcnt lgkmcnt(1)
	v_mfma_f32_16x16x32_bf16 v[32:35], v[24:27], v[4:7], v[32:35]
	v_mfma_f32_16x16x32_bf16 v[16:19], v[24:27], v[12:15], v[16:19]
	s_waitcnt lgkmcnt(0)
	v_mfma_f32_16x16x32_bf16 v[24:27], v[28:31], v[4:7], v[36:39]
	v_mfma_f32_16x16x32_bf16 v[20:23], v[28:31], v[12:15], v[20:23]
	v_max_i32_e32 v28, 0, v116
	v_lshl_add_u32 v28, v28, 2, v181
	ds_read2st64_b32 v[28:29], v28 offset0:132 offset1:197
	v_add_u32_e32 v30, -16, v116
	v_max_i32_e32 v30, 0, v30
	v_lshl_add_u32 v30, v30, 2, v181
	ds_read2st64_b32 v[30:31], v30 offset0:132 offset1:197
	s_waitcnt lgkmcnt(1)
	v_fmamk_f32 v28, v32, 0x3e38aa3b, v28
	v_subrev_u32_e32 v32, 32, v116
	v_max_i32_e32 v32, 0, v32
	v_lshl_add_u32 v32, v32, 2, v181
	s_waitcnt lgkmcnt(0)
	v_fmamk_f32 v30, v33, 0x3e38aa3b, v30
	ds_read2st64_b32 v[32:33], v32 offset0:132 offset1:197
	v_fmac_f32_e32 v29, 0x3e38aa3b, v16
	v_fmac_f32_e32 v31, 0x3e38aa3b, v17
	v_sub_f32_e32 v16, v29, v155
	v_sub_f32_e32 v17, v31, v155
	s_waitcnt lgkmcnt(0)
	v_fmamk_f32 v32, v34, 0x3e38aa3b, v32
	v_subrev_u32_e32 v34, 48, v116
	v_max_i32_e32 v34, 0, v34
	v_lshl_add_u32 v34, v34, 2, v181
	ds_read2st64_b32 v[36:37], v34 offset0:132 offset1:197
	v_add_u32_e32 v34, 0xffffff00, v116
	v_max_i32_e32 v34, 0, v34
	v_lshl_add_u32 v34, v34, 2, v181
	v_fmac_f32_e32 v33, 0x3e38aa3b, v18
	s_waitcnt lgkmcnt(0)
	v_fmamk_f32 v36, v35, 0x3e38aa3b, v36
	ds_read2st64_b32 v[34:35], v34 offset0:132 offset1:197
	v_fmac_f32_e32 v37, 0x3e38aa3b, v19
	v_sub_f32_e32 v18, v33, v155
	v_sub_f32_e32 v19, v37, v155
	v_exp_f32_e32 v18, v18
	s_waitcnt lgkmcnt(0)
	v_fmamk_f32 v34, v24, 0x3e38aa3b, v34
	v_add_u32_e32 v24, 0xfffffef0, v116
	v_max_i32_e32 v24, 0, v24
	v_lshl_add_u32 v24, v24, 2, v181
	ds_read2st64_b32 v[38:39], v24 offset0:132 offset1:197
	v_add_u32_e32 v24, 0xfffffee0, v116
	v_max_i32_e32 v24, 0, v24
	v_lshl_add_u32 v24, v24, 2, v181
	v_exp_f32_e32 v19, v19
	s_waitcnt lgkmcnt(0)
	v_fmamk_f32 v38, v25, 0x3e38aa3b, v38
	ds_read2st64_b32 v[24:25], v24 offset0:132 offset1:197
	v_fmac_f32_e32 v35, 0x3e38aa3b, v20
	v_fmac_f32_e32 v39, 0x3e38aa3b, v21
	v_pk_mul_f32 v[112:113], v[158:159], v[18:19]
	v_sub_f32_e32 v18, v35, v155
	s_waitcnt lgkmcnt(0)
	v_fmamk_f32 v24, v26, 0x3e38aa3b, v24
	v_add_u32_e32 v26, 0xfffffed0, v116
	v_max_i32_e32 v26, 0, v26
	v_lshl_add_u32 v26, v26, 2, v181
	ds_read2st64_b32 v[44:45], v26 offset0:132 offset1:197
	v_sub_f32_e32 v26, v28, v154
	v_sub_f32_e32 v28, v32, v154
	v_exp_f32_e32 v40, v28
	v_sub_f32_e32 v28, v36, v154
	v_exp_f32_e32 v41, v28
	v_sub_f32_e32 v19, v39, v155
	v_exp_f32_e32 v18, v18
	v_exp_f32_e32 v19, v19
	v_sub_f32_e32 v28, v34, v154
	v_pk_mul_f32 v[104:105], v[156:157], v[40:41]
	v_exp_f32_e32 v40, v28
	v_sub_f32_e32 v28, v38, v154
	v_exp_f32_e32 v41, v28
	v_fmac_f32_e32 v25, 0x3e38aa3b, v22
	s_waitcnt lgkmcnt(0)
	v_fmac_f32_e32 v45, 0x3e38aa3b, v23
	v_exp_f32_e32 v16, v16
	v_exp_f32_e32 v17, v17
	v_pk_mul_f32 v[110:111], v[158:159], v[18:19]
	v_sub_f32_e32 v18, v25, v155
	v_sub_f32_e32 v19, v45, v155
	v_fmamk_f32 v42, v27, 0x3e38aa3b, v44
	v_sub_f32_e32 v27, v30, v154
	v_exp_f32_e32 v18, v18
	v_exp_f32_e32 v19, v19
	v_exp_f32_e32 v26, v26
	v_exp_f32_e32 v27, v27
	v_sub_f32_e32 v24, v24, v154
	v_pk_mul_f32 v[106:107], v[156:157], v[40:41]
	v_exp_f32_e32 v40, v24
	v_sub_f32_e32 v24, v42, v154
	v_exp_f32_e32 v41, v24
	v_pk_mul_f32 v[16:17], v[158:159], v[16:17]
	v_pk_mul_f32 v[114:115], v[158:159], v[18:19]
	v_add_f32_e32 v18, v16, v17
	v_cvt_pk_bf16_f32 v44, v16, v17
	v_mul_u32_u24_e32 v16, 0x44, v120
	v_pk_mul_f32 v[26:27], v[156:157], v[26:27]
	v_lshlrev_b32_e32 v16, 1, v16
	v_lshlrev_b32_e32 v17, 3, v121
	v_add_f32_e32 v24, v26, v27
	v_add3_u32 v16, s72, v16, v17
	v_pk_mul_f32 v[108:109], v[156:157], v[40:41]
	v_add_f32_e32 v24, v104, v24
	v_cvt_pk_bf16_f32 v41, v104, v105
	v_add_f32_e32 v18, v112, v18
	v_cvt_pk_bf16_f32 v45, v112, v113
	v_add_u32_e32 v104, 0x4000, v16
	v_add_u32_e32 v112, 0x4800, v16
	v_add_u32_e32 v120, 0x5000, v16
	ds_read2_b64 v[20:23], v104 offset1:4
	ds_read2_b64 v[28:31], v112 offset0:16 offset1:20
	ds_read2_b64 v[36:39], v120 offset0:32 offset1:36
	v_add_u32_e32 v121, 0x5800, v16
	ds_read2_b64 v[122:125], v121 offset0:48 offset1:52
	v_fmac_f32_e32 v24, 0.5, v105
	v_add_f32_e32 v24, 0, v24
	v_cvt_pk_bf16_f32 v40, v26, v27
	v_cvt_pk_bf16_f32 v42, v106, v107
	v_cvt_pk_bf16_f32 v43, v108, v109
	v_fmac_f32_e32 v18, 0.5, v113
	v_cvt_pk_bf16_f32 v46, v110, v111
	v_cvt_pk_bf16_f32 v47, v114, v115
	v_add_f32_e32 v127, v24, v18
	s_waitcnt lgkmcnt(3)
; __device__ __forceinline__ f32x4 mfma16(bf16x8 a, bf16x8 b, f32x4 c) { return __builtin_amdgcn_mfma_f32_16x16x32_bf16(a, b, c, 0, 0, 0); }
; template <int MODE>
; __device__ __forceinline__ void nsa_compute(int cur, int buf, int t, int hl, u64 mymask, const bf16x8 (&Qf)[2][2], f32x4 (&O)[4][2], float (&m)[2], float (&l)[2],
;                                             const float (&inv)[2], float* impw, char* lds) {
;     ...
; #pragma unroll
;     for (int ks = 0; ks < 2; ++ks)
; #pragma unroll
;       for (int kk = 0; kk < 2; ++kk) kfr[ks][kk] = *(const bf16x8*)(kt + (32 * s2 + 16 * kk + fr) * 128 + (((ks * 4 + fq) ^ (fr & 7)) << 4));
;     __builtin_amdgcn_s_setprio(1);
; #pragma unroll
;     for (int ks = 0; ks < 2; ++ks)
; #pragma unroll
;       for (int kk = 0; kk < 2; ++kk)
; #pragma unroll
;         for (int r = 0; r < 2; ++r) S[kk][r] = mfma16(kfr[ks][kk], Qf[r][ks], S[kk][r]);
;     __builtin_amdgcn_s_setprio(0);
;     bf16x8 Pf[2];
;     float g1s[2] = {0.f, 0.f}, p3s[2] = {0.f, 0.f};
; #pragma unroll
;     for (int r = 0; r < 2; ++r) {
;       float sv[2][4];
; #pragma unroll
;       for (int kk = 0; kk < 2; ++kk)
; #pragma unroll
;         for (int e = 0; e < 4; ++e) {
;           const int off = 32 * s2 + 16 * kk + e;
;           int idx;
;           if (MODE <= 1) { idx = base - 16 * off; idx = idx > 0 ? idx : 0; } else idx = base - off;
;           sv[kk][e] = S[kk][r][e] * (0.125f * LOG2E) + tb[r * TS + idx];
;         }
;       float pv[2][4];
;       if (MODE == 1) {
; #pragma unroll
;         for (int kk = 0; kk < 2; ++kk)
; #pragma unroll
;           for (int e = 0; e < 4; ++e) pv[kk][e] = __builtin_amdgcn_exp2f(sv[kk][e] - m[r]) * inv[r];
; #pragma unroll
;         for (int kk = 0; kk < 2; ++kk) { g1s[kk] += pv[kk][0] + pv[kk][1] + pv[kk][2] + 0.5f * pv[kk][3]; p3s[kk] += 0.5f * pv[kk][3]; }
;     ...
;       __builtin_amdgcn_s_setprio(1);
; #pragma unroll
;       for (int df = 0; df < 4; ++df)
; #pragma unroll
;         for (int r = 0; r < 2; ++r) O[df][r] = mfma16(vfr[df], Pf[r], O[df][r]);
;       __builtin_amdgcn_s_setprio(0);
;     }
;     if (MODE == 1) {
; #pragma unroll
;       for (int kk = 0; kk < 2; ++kk) {
;         const int j = cur * 16 + (2 * s2 + kk) * 4 + fq;
;         atomicAdd(&impw[fr * 65 + j], g1s[kk]);
;         if (j + 1 < 64) atomicAdd(&impw[fr * 65 + j + 1], p3s[kk]);
;       }
;     }
	v_mfma_f32_16x16x32_bf16 v[16:19], v[20:23], v[40:43], v[88:91]
	v_mfma_f32_16x16x32_bf16 v[20:23], v[20:23], v[44:47], v[96:99]
	s_waitcnt lgkmcnt(2)
	v_mfma_f32_16x16x32_bf16 v[24:27], v[28:31], v[40:43], v[100:103]
	v_mfma_f32_16x16x32_bf16 v[28:31], v[28:31], v[44:47], v[84:87]
	s_waitcnt lgkmcnt(1)
	v_mfma_f32_16x16x32_bf16 v[32:35], v[36:39], v[40:43], v[92:95]
	v_mfma_f32_16x16x32_bf16 v[36:39], v[36:39], v[44:47], v[76:79]
	s_waitcnt lgkmcnt(0)
	v_mfma_f32_16x16x32_bf16 v[40:43], v[122:125], v[40:43], v[80:83]
	v_mfma_f32_16x16x32_bf16 v[44:47], v[122:125], v[44:47], v[72:75]
	v_lshlrev_b32_e32 v122, 2, v160
	v_lshlrev_b32_e32 v123, 2, v126
	v_add3_u32 v161, v184, v122, v123
	ds_add_f32 v161, v127
	v_cmp_gt_u32_e32 vcc, 63, v160
	s_and_saveexec_b64 s[16:17], vcc
	v_mul_f32_e32 v105, 0.5, v105
	v_mul_f32_e32 v113, 0.5, v113
	v_add_f32_e32 v105, 0, v105
	v_add_f32_e32 v105, v105, v113
	ds_add_f32 v161, v105 offset:4
	s_or_b64 exec, exec, s[16:17]
	v_add_f32_e32 v105, v106, v107
	v_add_f32_e32 v105, v108, v105
	v_add_f32_e32 v106, v110, v111
	v_fmac_f32_e32 v105, 0.5, v109
	v_add_f32_e32 v106, v114, v106
	v_add_f32_e32 v105, 0, v105
	v_fmac_f32_e32 v106, 0.5, v115
	v_add_f32_e32 v105, v105, v106
	ds_add_f32 v161, v105 offset:16
	v_or_b32_e32 v105, 4, v160
	v_cmp_gt_u32_e32 vcc, 63, v105
	s_and_saveexec_b64 s[16:17], vcc
	v_mul_f32_e32 v105, 0.5, v109
	v_mul_f32_e32 v106, 0.5, v115
	v_add_f32_e32 v105, 0, v105
	v_add_f32_e32 v105, v105, v106
	ds_add_f32 v161, v105 offset:20
	s_or_b64 exec, exec, s[16:17]
	v_add_u32_e32 v105, v118, v117
	ds_read_b128 v[106:109], v105 offset:4096
	ds_read_b128 v[122:125], v105 offset:6144
	v_add_u32_e32 v105, v119, v117
	ds_read_b128 v[126:129], v105 offset:4096
	ds_read_b128 v[130:133], v105 offset:6144
	s_waitcnt lgkmcnt(3)
	v_mfma_f32_16x16x32_bf16 v[134:137], v[106:109], v[0:3], 0
	v_mfma_f32_16x16x32_bf16 v[106:109], v[106:109], v[8:11], 0
	s_waitcnt lgkmcnt(2)
	v_mfma_f32_16x16x32_bf16 v[138:141], v[122:125], v[0:3], 0
	v_mfma_f32_16x16x32_bf16 v[122:125], v[122:125], v[8:11], 0
	s_waitcnt lgkmcnt(1)
	v_mfma_f32_16x16x32_bf16 v[134:137], v[126:129], v[4:7], v[134:137]
	v_mfma_f32_16x16x32_bf16 v[106:109], v[126:129], v[12:15], v[106:109]
	s_waitcnt lgkmcnt(0)
	v_mfma_f32_16x16x32_bf16 v[126:129], v[130:133], v[4:7], v[138:141]
	v_mfma_f32_16x16x32_bf16 v[122:125], v[130:133], v[12:15], v[122:125]
	v_add_u32_e32 v105, 0xfffffe00, v116
	v_max_i32_e32 v105, 0, v105
	v_lshl_add_u32 v105, v105, 2, v181
	ds_read2st64_b32 v[110:111], v105 offset0:132 offset1:197
	v_add_u32_e32 v117, 0xfffffd00, v116
	v_max_i32_e32 v117, 0, v117
	v_lshl_add_u32 v117, v117, 2, v181
	v_add_u32_e32 v113, 0xfffffde0, v116
	s_waitcnt lgkmcnt(0)
	v_fmamk_f32 v105, v134, 0x3e38aa3b, v110
	v_add_u32_e32 v110, 0xfffffdf0, v116
	v_max_i32_e32 v110, 0, v110
	v_lshl_add_u32 v110, v110, 2, v181
	ds_read2st64_b32 v[114:115], v110 offset0:132 offset1:197
	ds_read2st64_b32 v[142:143], v117 offset0:132 offset1:197
	v_add_u32_e32 v117, 0xfffffcf0, v116
	v_max_i32_e32 v113, 0, v113
	v_max_i32_e32 v117, 0, v117
	s_waitcnt lgkmcnt(1)
	v_fmamk_f32 v110, v135, 0x3e38aa3b, v114
	v_add_u32_e32 v114, 0xfffffdd0, v116
	v_max_i32_e32 v114, 0, v114
	v_lshl_add_u32 v113, v113, 2, v181
	v_lshl_add_u32 v114, v114, 2, v181
	v_lshl_add_u32 v117, v117, 2, v181
	ds_read2st64_b32 v[118:119], v113 offset0:132 offset1:197
	ds_read2st64_b32 v[130:131], v114 offset0:132 offset1:197
	ds_read2st64_b32 v[146:147], v117 offset0:132 offset1:197
	v_add_u32_e32 v117, 0xfffffce0, v116
	v_max_i32_e32 v117, 0, v117
	v_add_u32_e32 v116, 0xfffffcd0, v116
	v_lshl_add_u32 v117, v117, 2, v181
	v_max_i32_e32 v116, 0, v116
	s_waitcnt lgkmcnt(2)
	v_fmamk_f32 v113, v136, 0x3e38aa3b, v118
	s_waitcnt lgkmcnt(1)
	v_fmamk_f32 v114, v137, 0x3e38aa3b, v130
	v_fmamk_f32 v118, v126, 0x3e38aa3b, v142
	s_waitcnt lgkmcnt(0)
	v_fmamk_f32 v130, v127, 0x3e38aa3b, v146
	ds_read2st64_b32 v[126:127], v117 offset0:132 offset1:197
	v_lshl_add_u32 v116, v116, 2, v181
	ds_read2st64_b32 v[116:117], v116 offset0:132 offset1:197
	v_fmac_f32_e32 v119, 0x3e38aa3b, v108
	v_fmac_f32_e32 v131, 0x3e38aa3b, v109
	v_sub_f32_e32 v105, v105, v154
	v_sub_f32_e32 v108, v119, v155
	v_sub_f32_e32 v109, v131, v155
	s_waitcnt lgkmcnt(1)
	v_fmamk_f32 v126, v128, 0x3e38aa3b, v126
	v_exp_f32_e32 v128, v105
	v_sub_f32_e32 v105, v110, v154
	v_exp_f32_e32 v108, v108
	v_exp_f32_e32 v109, v109
	s_waitcnt lgkmcnt(0)
; template <int MODE>
; __device__ __forceinline__ void nsa_compute(int cur, int buf, int t, int hl, u64 mymask, const bf16x8 (&Qf)[2][2], f32x4 (&O)[4][2], float (&m)[2], float (&l)[2],
;                                             const float (&inv)[2], float* impw, char* lds) {
;     ...
;       float pv[2][4];
;       if (MODE == 1) {
; #pragma unroll
;         for (int kk = 0; kk < 2; ++kk)
; #pragma unroll
;           for (int e = 0; e < 4; ++e) pv[kk][e] = __builtin_amdgcn_exp2f(sv[kk][e] - m[r]) * inv[r];
; #pragma unroll
;         for (int kk = 0; kk < 2; ++kk) { g1s[kk] += pv[kk][0] + pv[kk][1] + pv[kk][2] + 0.5f * pv[kk][3]; p3s[kk] += 0.5f * pv[kk][3]; }
;       } else {
;         const float mxa = fmaxf(fmaxf(sv[0][0], sv[0][1]), sv[0][2]), mxb = fmaxf(fmaxf(sv[0][3], sv[1][0]), sv[1][1]);
;         float mx = fmaxf(fmaxf(fmaxf(sv[1][2], sv[1][3]), mxa), mxb);
;         if (MODE == 2) mx = selok ? mx : -__builtin_inff();
;         if (__any(mx > m[r] + 8.0f)) {
;           mx = fmaxf(mx, __shfl_xor(mx, 16)); mx = fmaxf(mx, __shfl_xor(mx, 32));
;           const float mn = fmaxf(m[r], mx), al = __builtin_amdgcn_exp2f(m[r] - mn);
;           m[r] = mn; l[r] *= al;
;           if (MODE != 0) {
; #pragma unroll
;             for (int df = 0; df < 4; ++df) O[df][r] *= al;
;           }
;         }
;         const float me = (MODE == 2) ? (selok ? m[r] : __builtin_inff()) : m[r];
;         float ps = 0.f;
; #pragma unroll
;         for (int kk = 0; kk < 2; ++kk)
; #pragma unroll
;           for (int e = 0; e < 4; ++e) { pv[kk][e] = __builtin_amdgcn_exp2f(sv[kk][e] - me); ps += pv[kk][e]; }
;         l[r] += ps;
;       }
;       if (MODE != 0) {
;         const unsigned w0 = pk2(pv[0][0], pv[0][1]), w1 = pk2(pv[0][2], pv[0][3]), w2 = pk2(pv[1][0], pv[1][1]), w3 = pk2(pv[1][2], pv[1][3]);
;         u32x4 pw; pw.x = w0; pw.y = w1; pw.z = w2; pw.w = w3;
;         Pf[r] = __builtin_bit_cast(bf16x8, pw);
;       }
;     }
;     if (MODE != 0) {
;       bf16x8 vfr[4];
; #pragma unroll
;       for (int df = 0; df < 4; ++df) {
;         const bf16x4 va = *(const bf16x4*)(vt + (df * 16 + fr) * 68 + 32 * s2 + 4 * fq);
;         const bf16x4 vb = *(const bf16x4*)(vt + (df * 16 + fr) * 68 + 32 * s2 + 16 + 4 * fq);
;         bf16x8 vf; vf[0] = va[0]; vf[1] = va[1]; vf[2] = va[2]; vf[3] = va[3]; vf[4] = vb[0]; vf[5] = vb[1]; vf[6] = vb[2]; vf[7] = vb[3];
	v_fmamk_f32 v116, v129, 0x3e38aa3b, v116
	v_exp_f32_e32 v129, v105
	v_sub_f32_e32 v105, v113, v154
	v_exp_f32_e32 v132, v105
	v_sub_f32_e32 v105, v114, v154
	v_exp_f32_e32 v133, v105
	v_fmac_f32_e32 v143, 0x3e38aa3b, v122
	v_fmac_f32_e32 v147, 0x3e38aa3b, v123
	v_pk_mul_f32 v[144:145], v[158:159], v[108:109]
	v_sub_f32_e32 v108, v143, v155
	v_sub_f32_e32 v109, v147, v155
	v_exp_f32_e32 v108, v108
	v_exp_f32_e32 v109, v109
	v_sub_f32_e32 v105, v118, v154
	v_pk_mul_f32 v[136:137], v[156:157], v[132:133]
	v_exp_f32_e32 v132, v105
	v_sub_f32_e32 v105, v130, v154
	v_fmac_f32_e32 v111, 0x3e38aa3b, v106
	v_fmac_f32_e32 v115, 0x3e38aa3b, v107
	v_exp_f32_e32 v133, v105
	v_fmac_f32_e32 v127, 0x3e38aa3b, v124
	v_fmac_f32_e32 v117, 0x3e38aa3b, v125
	v_sub_f32_e32 v106, v111, v155
	v_sub_f32_e32 v107, v115, v155
	v_exp_f32_e32 v106, v106
	v_exp_f32_e32 v107, v107
	v_pk_mul_f32 v[142:143], v[158:159], v[108:109]
	v_sub_f32_e32 v108, v127, v155
	v_sub_f32_e32 v109, v117, v155
	v_exp_f32_e32 v108, v108
	v_exp_f32_e32 v109, v109
	v_sub_f32_e32 v105, v126, v154
	v_pk_mul_f32 v[128:129], v[156:157], v[128:129]
	v_pk_mul_f32 v[138:139], v[156:157], v[132:133]
	v_exp_f32_e32 v132, v105
	v_sub_f32_e32 v105, v116, v154
	v_exp_f32_e32 v133, v105
	v_add_f32_e32 v105, v128, v129
	v_pk_mul_f32 v[106:107], v[158:159], v[106:107]
	v_add_f32_e32 v105, v136, v105
	v_pk_mul_f32 v[146:147], v[158:159], v[108:109]
	v_add_f32_e32 v108, v106, v107
	v_fmac_f32_e32 v105, 0.5, v137
	v_add_f32_e32 v108, v144, v108
	v_add_f32_e32 v105, 0, v105
	v_fmac_f32_e32 v108, 0.5, v145
	v_pk_mul_f32 v[140:141], v[156:157], v[132:133]
	v_cvt_pk_bf16_f32 v133, v136, v137
	v_add_f32_e32 v136, v105, v108
	ds_read2_b64 v[108:111], v104 offset0:8 offset1:12
	ds_read2_b64 v[112:115], v112 offset0:24 offset1:28
	ds_read2_b64 v[116:119], v120 offset0:40 offset1:44
	ds_read2_b64 v[120:123], v121 offset0:56 offset1:60
	v_cvt_pk_bf16_f32 v132, v128, v129
	v_cvt_pk_bf16_f32 v134, v138, v139
	v_cvt_pk_bf16_f32 v135, v140, v141
	v_cvt_pk_bf16_f32 v162, v106, v107
	v_cvt_pk_bf16_f32 v163, v144, v145
	v_cvt_pk_bf16_f32 v164, v142, v143
	v_cvt_pk_bf16_f32 v165, v146, v147
	s_waitcnt lgkmcnt(3)
	v_mfma_f32_16x16x32_bf16 v[104:107], v[108:111], v[132:135], v[16:19]
	v_mfma_f32_16x16x32_bf16 v[108:111], v[108:111], v[162:165], v[20:23]
	s_waitcnt lgkmcnt(2)
	v_mfma_f32_16x16x32_bf16 v[124:127], v[112:115], v[132:135], v[24:27]
	v_mfma_f32_16x16x32_bf16 v[112:115], v[112:115], v[162:165], v[28:31]
	s_waitcnt lgkmcnt(1)
	v_mfma_f32_16x16x32_bf16 v[128:131], v[116:119], v[132:135], v[32:35]
	v_mfma_f32_16x16x32_bf16 v[116:119], v[116:119], v[162:165], v[36:39]
	s_waitcnt lgkmcnt(0)
	v_mfma_f32_16x16x32_bf16 v[132:135], v[120:123], v[132:135], v[40:43]
	v_mfma_f32_16x16x32_bf16 v[120:123], v[120:123], v[162:165], v[44:47]
	ds_add_f32 v161, v136 offset:32
	v_or_b32_e32 v16, 8, v160
	v_cmp_gt_u32_e32 vcc, 63, v16
	s_and_saveexec_b64 s[16:17], vcc
	v_mul_f32_e32 v16, 0.5, v137
	v_mul_f32_e32 v17, 0.5, v145
	v_add_f32_e32 v16, 0, v16
	v_add_f32_e32 v16, v16, v17
	ds_add_f32 v161, v16 offset:36
	s_or_b64 exec, exec, s[16:17]
	v_add_f32_e32 v16, v138, v139
	v_add_f32_e32 v16, v140, v16
	v_add_f32_e32 v17, v142, v143
	v_fmac_f32_e32 v16, 0.5, v141
	v_add_f32_e32 v17, v146, v17
	v_add_f32_e32 v16, 0, v16
	v_fmac_f32_e32 v17, 0.5, v147
	v_add_f32_e32 v16, v16, v17
	ds_add_f32 v161, v16 offset:48
	v_or_b32_e32 v16, 12, v160
	v_cmp_gt_u32_e32 vcc, 63, v16
	s_and_saveexec_b64 s[16:17], vcc
	v_mul_f32_e32 v16, 0.5, v141
	v_mul_f32_e32 v17, 0.5, v147
	v_add_f32_e32 v16, 0, v16
	v_add_f32_e32 v16, v16, v17
	ds_add_f32 v161, v16 offset:52
	s_or_b64 exec, exec, s[16:17]
	s_cmp_lt_i32 s66, 0
	s_cbranch_scc1 .LBB0_313
	v_mov_b32 v16, v179
	s_nop 0
	v_ashrrev_i32_e32 v17, 3, v16
	v_xor_b32_e32 v19, v17, v16
	v_lshlrev_b32_e32 v16, 3, v16
	v_lshlrev_b32_e32 v19, 4, v19
	v_and_b32_e32 v16, 56, v16
	v_lshlrev_b32_e32 v18, 7, v17
	v_and_b32_e32 v19, 0x70, v19
	v_mul_u32_u24_e32 v16, 0x88, v16
	v_lshlrev_b32_e32 v17, 1, v17
	v_add3_u32 v18, s71, v18, v19
	v_add3_u32 v16, s70, v16, v17
	ds_write_b128 v18, v[64:67]
	ds_write_b16 v16, v68 offset:16384
	ds_write_b16_d16_hi v16, v68 offset:16520
	ds_write_b16 v16, v69 offset:16656
	ds_write_b16_d16_hi v16, v69 offset:16792
	ds_write_b16 v16, v70 offset:16928
	ds_write_b16_d16_hi v16, v70 offset:17064
	ds_write_b16 v16, v71 offset:17200
	ds_write_b16_d16_hi v16, v71 offset:17336

; template <int MODE>
; __device__ __forceinline__ void nsa_compute(int cur, int buf, int t, int hl, u64 mymask, const bf16x8 (&Qf)[2][2], f32x4 (&O)[4][2], float (&m)[2], float (&l)[2],
;                                             const float (&inv)[2], float* impw, char* lds) {
;     ...
; #pragma unroll
;     for (int ks = 0; ks < 2; ++ks)
; #pragma unroll
;       for (int kk = 0; kk < 2; ++kk) kfr[ks][kk] = *(const bf16x8*)(kt + (32 * s2 + 16 * kk + fr) * 128 + (((ks * 4 + fq) ^ (fr & 7)) << 4));
;     __builtin_amdgcn_s_setprio(1);
; #pragma unroll
;     for (int ks = 0; ks < 2; ++ks)
; #pragma unroll
;       for (int kk = 0; kk < 2; ++kk)
; #pragma unroll
;         for (int r = 0; r < 2; ++r) S[kk][r] = mfma16(kfr[ks][kk], Qf[r][ks], S[kk][r]);
;     __builtin_amdgcn_s_setprio(0);
;     bf16x8 Pf[2];
;     float g1s[2] = {0.f, 0.f}, p3s[2] = {0.f, 0.f};
; #pragma unroll
;     for (int r = 0; r < 2; ++r) {
;       float sv[2][4];
; #pragma unroll
;       for (int kk = 0; kk < 2; ++kk)
; #pragma unroll
;         for (int e = 0; e < 4; ++e) {
;           const int off = 32 * s2 + 16 * kk + e;
;           int idx;
;           if (MODE <= 1) { idx = base - 16 * off; idx = idx > 0 ? idx : 0; } else idx = base - off;
;           sv[kk][e] = S[kk][r][e] * (0.125f * LOG2E) + tb[r * TS + idx];
;         }
;       float pv[2][4];
;       if (MODE == 1) {
; #pragma unroll
;         for (int kk = 0; kk < 2; ++kk)
; #pragma unroll
;           for (int e = 0; e < 4; ++e) pv[kk][e] = __builtin_amdgcn_exp2f(sv[kk][e] - m[r]) * inv[r];
; #pragma unroll
;         for (int kk = 0; kk < 2; ++kk) { g1s[kk] += pv[kk][0] + pv[kk][1] + pv[kk][2] + 0.5f * pv[kk][3]; p3s[kk] += 0.5f * pv[kk][3]; }
;       } else {
;         const float mxa = fmaxf(fmaxf(sv[0][0], sv[0][1]), sv[0][2]), mxb = fmaxf(fmaxf(sv[0][3], sv[1][0]), sv[1][1]);
;         float mx = fmaxf(fmaxf(fmaxf(sv[1][2], sv[1][3]), mxa), mxb);
;         if (MODE == 2) mx = selok ? mx : -__builtin_inff();
;         if (__any(mx > m[r] + 8.0f)) {
;           mx = fmaxf(mx, __shfl_xor(mx, 16)); mx = fmaxf(mx, __shfl_xor(mx, 32));
;           const float mn = fmaxf(m[r], mx), al = __builtin_amdgcn_exp2f(m[r] - mn);
;           m[r] = mn; l[r] *= al;
;           if (MODE != 0) {
; #pragma unroll
;             for (int df = 0; df < 4; ++df) O[df][r] *= al;
;           }
;         }
.LBB0_315:
	s_mov_b64 s[36:37], -1
	s_cmp_lt_i32 s66, 0
	s_mov_b64 s[42:43], -1
	s_cbranch_scc1 .LBB0_329
	v_mov_b32 v16, v179
	s_nop 0
	v_lshrrev_b32_e32 v17, 4, v16
	v_bfe_u32 v139, v16, 4, 2
	v_and_b32_e32 v24, 7, v16
	v_and_b32_e32 v138, 15, v16
	v_bitop3_b32 v16, v17, v24, 3 bitop3:0x6c
	v_bitop3_b32 v24, v139, v24, 4 bitop3:0x36
	v_lshlrev_b32_e32 v25, 7, v138
	v_lshl_add_u32 v16, v16, 4, s71
	v_lshl_add_u32 v24, v24, 4, s71
	v_add_u32_e32 v161, v16, v25
	v_add_u32_e32 v162, v24, v25
	ds_read_b128 v[16:19], v161
	ds_read_b128 v[20:23], v161 offset:2048
	ds_read_b128 v[24:27], v162
	ds_read_b128 v[28:31], v162 offset:2048
	v_lshlrev_b32_e32 v32, 6, v139
	v_lshl_or_b32 v32, s66, 10, v32
	v_sub_u32_e32 v160, v183, v32
	v_lshl_or_b32 v176, s66, 4, v139
	v_mul_u32_u24_e32 v163, 0x41, v138
	s_waitcnt lgkmcnt(3)
	v_mfma_f32_16x16x32_bf16 v[32:35], v[16:19], v[0:3], 0
	v_mfma_f32_16x16x32_bf16 v[16:19], v[16:19], v[8:11], 0
	s_waitcnt lgkmcnt(2)
	v_mfma_f32_16x16x32_bf16 v[36:39], v[20:23], v[0:3], 0
	v_mfma_f32_16x16x32_bf16 v[20:23], v[20:23], v[8:11], 0
	s_waitcnt lgkmcnt(1)
	v_mfma_f32_16x16x32_bf16 v[32:35], v[24:27], v[4:7], v[32:35]
	v_mfma_f32_16x16x32_bf16 v[16:19], v[24:27], v[12:15], v[16:19]
	s_waitcnt lgkmcnt(0)
	v_mfma_f32_16x16x32_bf16 v[24:27], v[28:31], v[4:7], v[36:39]
	v_mfma_f32_16x16x32_bf16 v[20:23], v[28:31], v[12:15], v[20:23]
	v_add_u32_e32 v29, -16, v160
	v_max_i32_e32 v28, 0, v160
	v_max_i32_e32 v29, 0, v29
	v_lshl_add_u32 v28, v28, 2, v181
	v_lshl_add_u32 v29, v29, 2, v181
	ds_read2st64_b32 v[36:37], v28 offset0:132 offset1:197
	ds_read2st64_b32 v[38:39], v29 offset0:132 offset1:197
	v_subrev_u32_e32 v30, 32, v160
	v_max_i32_e32 v30, 0, v30
	v_lshl_add_u32 v30, v30, 2, v181
	s_waitcnt lgkmcnt(1)
	v_fmamk_f32 v28, v32, 0x3e38aa3b, v36
	s_waitcnt lgkmcnt(0)
	v_fmamk_f32 v29, v33, 0x3e38aa3b, v38
	ds_read2st64_b32 v[32:33], v30 offset0:132 offset1:197
	v_subrev_u32_e32 v31, 48, v160
	v_max_i32_e32 v31, 0, v31
	v_lshl_add_u32 v31, v31, 2, v181
	ds_read2st64_b32 v[42:43], v31 offset0:132 offset1:197
	s_waitcnt lgkmcnt(1)
	v_fmamk_f32 v30, v34, 0x3e38aa3b, v32
	v_add_u32_e32 v32, 0xffffff00, v160
	v_max_i32_e32 v32, 0, v32
	v_lshl_add_u32 v32, v32, 2, v181
	s_waitcnt lgkmcnt(0)
	v_fmamk_f32 v31, v35, 0x3e38aa3b, v42
	ds_read2st64_b32 v[34:35], v32 offset0:132 offset1:197
	v_fmac_f32_e32 v33, 0x3e38aa3b, v18
	v_fmac_f32_e32 v43, 0x3e38aa3b, v19
	v_sub_f32_e32 v18, v33, v155
	v_sub_f32_e32 v19, v43, v155
	s_waitcnt lgkmcnt(0)
	v_fmamk_f32 v32, v24, 0x3e38aa3b, v34
	v_add_u32_e32 v24, 0xfffffef0, v160
	v_max_i32_e32 v24, 0, v24
	v_lshl_add_u32 v24, v24, 2, v181
	ds_read2st64_b32 v[46:47], v24 offset0:132 offset1:197
	v_add_u32_e32 v24, 0xfffffee0, v160
	v_max_i32_e32 v24, 0, v24
	v_lshl_add_u32 v24, v24, 2, v181
	v_exp_f32_e32 v18, v18
	s_waitcnt lgkmcnt(0)
	v_fmamk_f32 v34, v25, 0x3e38aa3b, v46
	ds_read2st64_b32 v[24:25], v24 offset0:132 offset1:197
	v_exp_f32_e32 v19, v19
	v_fmac_f32_e32 v35, 0x3e38aa3b, v20
	v_fmac_f32_e32 v47, 0x3e38aa3b, v21
	v_fmac_f32_e32 v37, 0x3e38aa3b, v16
	s_waitcnt lgkmcnt(0)
	v_fmamk_f32 v24, v26, 0x3e38aa3b, v24
	v_add_u32_e32 v26, 0xfffffed0, v160
	v_max_i32_e32 v26, 0, v26
	v_lshl_add_u32 v26, v26, 2, v181
	ds_read2st64_b32 v[136:137], v26 offset0:132 offset1:197
	v_pk_mul_f32 v[44:45], v[158:159], v[18:19]
	v_sub_f32_e32 v18, v35, v155
	v_sub_f32_e32 v19, v47, v155
	v_exp_f32_e32 v18, v18
	v_exp_f32_e32 v19, v19
	v_fmac_f32_e32 v39, 0x3e38aa3b, v17
	v_fmac_f32_e32 v25, 0x3e38aa3b, v22
	s_waitcnt lgkmcnt(0)
	v_fmac_f32_e32 v137, 0x3e38aa3b, v23
	v_sub_f32_e32 v16, v37, v155
	v_sub_f32_e32 v17, v39, v155
	v_exp_f32_e32 v16, v16
	v_exp_f32_e32 v17, v17
	v_pk_mul_f32 v[42:43], v[158:159], v[18:19]
	v_sub_f32_e32 v18, v25, v155
	v_sub_f32_e32 v19, v137, v155
	v_fmamk_f32 v36, v27, 0x3e38aa3b, v136
	v_sub_f32_e32 v26, v28, v154
	v_sub_f32_e32 v27, v29, v154
	v_exp_f32_e32 v18, v18
	v_exp_f32_e32 v19, v19
	v_exp_f32_e32 v26, v26
	v_exp_f32_e32 v27, v27
	v_sub_f32_e32 v28, v30, v154
	v_sub_f32_e32 v29, v31, v154
	v_exp_f32_e32 v28, v28
	v_exp_f32_e32 v29, v29
	v_pk_mul_f32 v[16:17], v[158:159], v[16:17]
	v_sub_f32_e32 v24, v24, v154
	v_pk_mul_f32 v[46:47], v[158:159], v[18:19]
	v_add_f32_e32 v18, v16, v17
	v_cvt_pk_bf16_f32 v144, v16, v17
	v_mul_u32_u24_e32 v16, 0x44, v138
	v_pk_mul_f32 v[26:27], v[156:157], v[26:27]
	v_exp_f32_e32 v40, v24
	v_sub_f32_e32 v24, v36, v154
	v_lshlrev_b32_e32 v16, 1, v16
	v_lshlrev_b32_e32 v17, 3, v139
	v_pk_mul_f32 v[28:29], v[156:157], v[28:29]
	v_sub_f32_e32 v30, v32, v154
	v_sub_f32_e32 v31, v34, v154
	v_exp_f32_e32 v41, v24
	v_add_f32_e32 v24, v26, v27
	v_add3_u32 v16, s70, v16, v17
	v_exp_f32_e32 v30, v30
	v_exp_f32_e32 v31, v31
	v_add_f32_e32 v24, v28, v24
	v_cvt_pk_bf16_f32 v141, v28, v29
	v_add_f32_e32 v18, v44, v18
	v_cvt_pk_bf16_f32 v145, v44, v45
	v_add_u32_e32 v28, 0x4000, v16
	v_add_u32_e32 v44, 0x4800, v16
	v_add_u32_e32 v189, 0x5000, v16
	ds_read2_b64 v[20:23], v28 offset1:4
	ds_read2_b64 v[32:35], v44 offset0:16 offset1:20
	ds_read2_b64 v[136:139], v189 offset0:32 offset1:36
	v_add_u32_e32 v190, 0x5800, v16
	ds_read2_b64 v[164:167], v190 offset0:48 offset1:52
	v_pk_mul_f32 v[30:31], v[156:157], v[30:31]
	v_pk_mul_f32 v[40:41], v[156:157], v[40:41]
	v_fmac_f32_e32 v24, 0.5, v29
	v_add_f32_e32 v24, 0, v24
	v_cvt_pk_bf16_f32 v140, v26, v27
	v_cvt_pk_bf16_f32 v142, v30, v31
	v_cvt_pk_bf16_f32 v143, v40, v41
	v_fmac_f32_e32 v18, 0.5, v45
	v_cvt_pk_bf16_f32 v146, v42, v43
	v_cvt_pk_bf16_f32 v147, v46, v47
	v_add_f32_e32 v168, v24, v18
	s_waitcnt lgkmcnt(3)
	v_mfma_f32_16x16x32_bf16 v[16:19], v[20:23], v[140:143], v[104:107]
	v_mfma_f32_16x16x32_bf16 v[20:23], v[20:23], v[144:147], v[108:111]
	s_waitcnt lgkmcnt(2)
; __device__ __forceinline__ f32x4 mfma16(bf16x8 a, bf16x8 b, f32x4 c) { return __builtin_amdgcn_mfma_f32_16x16x32_bf16(a, b, c, 0, 0, 0); }
; template <int MODE>
; __device__ __forceinline__ void nsa_compute(int cur, int buf, int t, int hl, u64 mymask, const bf16x8 (&Qf)[2][2], f32x4 (&O)[4][2], float (&m)[2], float (&l)[2],
;                                             const float (&inv)[2], float* impw, char* lds) {
;     ...
; #pragma unroll
;     for (int ks = 0; ks < 2; ++ks)
; #pragma unroll
;       for (int kk = 0; kk < 2; ++kk) kfr[ks][kk] = *(const bf16x8*)(kt + (32 * s2 + 16 * kk + fr) * 128 + (((ks * 4 + fq) ^ (fr & 7)) << 4));
;     __builtin_amdgcn_s_setprio(1);
; #pragma unroll
;     for (int ks = 0; ks < 2; ++ks)
; #pragma unroll
;       for (int kk = 0; kk < 2; ++kk)
; #pragma unroll
;         for (int r = 0; r < 2; ++r) S[kk][r] = mfma16(kfr[ks][kk], Qf[r][ks], S[kk][r]);
;     __builtin_amdgcn_s_setprio(0);
;     bf16x8 Pf[2];
;     float g1s[2] = {0.f, 0.f}, p3s[2] = {0.f, 0.f};
; #pragma unroll
;     for (int r = 0; r < 2; ++r) {
;       float sv[2][4];
; #pragma unroll
;       for (int kk = 0; kk < 2; ++kk)
; #pragma unroll
;         for (int e = 0; e < 4; ++e) {
;           const int off = 32 * s2 + 16 * kk + e;
;           int idx;
;           if (MODE <= 1) { idx = base - 16 * off; idx = idx > 0 ? idx : 0; } else idx = base - off;
;           sv[kk][e] = S[kk][r][e] * (0.125f * LOG2E) + tb[r * TS + idx];
;         }
;       float pv[2][4];
;       if (MODE == 1) {
; #pragma unroll
;         for (int kk = 0; kk < 2; ++kk)
; #pragma unroll
;           for (int e = 0; e < 4; ++e) pv[kk][e] = __builtin_amdgcn_exp2f(sv[kk][e] - m[r]) * inv[r];
; #pragma unroll
;         for (int kk = 0; kk < 2; ++kk) { g1s[kk] += pv[kk][0] + pv[kk][1] + pv[kk][2] + 0.5f * pv[kk][3]; p3s[kk] += 0.5f * pv[kk][3]; }
;     ...
;       __builtin_amdgcn_s_setprio(1);
; #pragma unroll
;       for (int df = 0; df < 4; ++df)
; #pragma unroll
;         for (int r = 0; r < 2; ++r) O[df][r] = mfma16(vfr[df], Pf[r], O[df][r]);
;       __builtin_amdgcn_s_setprio(0);
;     }
;     if (MODE == 1) {
; #pragma unroll
;       for (int kk = 0; kk < 2; ++kk) {
;         const int j = cur * 16 + (2 * s2 + kk) * 4 + fq;
;         atomicAdd(&impw[fr * 65 + j], g1s[kk]);
;         if (j + 1 < 64) atomicAdd(&impw[fr * 65 + j + 1], p3s[kk]);
;       }
;     }
	v_mfma_f32_16x16x32_bf16 v[24:27], v[32:35], v[140:143], v[124:127]
	v_mfma_f32_16x16x32_bf16 v[32:35], v[32:35], v[144:147], v[112:115]
	s_waitcnt lgkmcnt(1)
	v_mfma_f32_16x16x32_bf16 v[36:39], v[136:139], v[140:143], v[128:131]
	v_mfma_f32_16x16x32_bf16 v[136:139], v[136:139], v[144:147], v[116:119]
	s_waitcnt lgkmcnt(0)
	v_mfma_f32_16x16x32_bf16 v[140:143], v[164:167], v[140:143], v[132:135]
	v_mfma_f32_16x16x32_bf16 v[144:147], v[164:167], v[144:147], v[120:123]
	v_lshlrev_b32_e32 v164, 2, v176
	v_lshlrev_b32_e32 v163, 2, v163
	v_add3_u32 v185, v184, v164, v163
	ds_add_f32 v185, v168
	v_cmp_gt_u32_e32 vcc, 63, v176
	s_and_saveexec_b64 s[16:17], vcc
	v_mul_f32_e32 v29, 0.5, v29
	v_mul_f32_e32 v45, 0.5, v45
	v_add_f32_e32 v29, 0, v29
	v_add_f32_e32 v29, v29, v45
	ds_add_f32 v185, v29 offset:4
	s_or_b64 exec, exec, s[16:17]
	v_add_f32_e32 v29, v30, v31
	v_add_f32_e32 v29, v40, v29
	v_add_f32_e32 v30, v42, v43
	v_fmac_f32_e32 v29, 0.5, v41
	v_add_f32_e32 v30, v46, v30
	v_add_f32_e32 v29, 0, v29
	v_fmac_f32_e32 v30, 0.5, v47
	v_add_f32_e32 v29, v29, v30
	ds_add_f32 v185, v29 offset:16
	v_or_b32_e32 v29, 4, v176
	v_cmp_gt_u32_e32 vcc, 63, v29
	s_and_saveexec_b64 s[16:17], vcc
	v_mul_f32_e32 v29, 0.5, v41
	v_mul_f32_e32 v30, 0.5, v47
	v_add_f32_e32 v29, 0, v29
	v_add_f32_e32 v29, v29, v30
	ds_add_f32 v185, v29 offset:20
	s_or_b64 exec, exec, s[16:17]
	ds_read_b128 v[40:43], v161 offset:4096
	ds_read_b128 v[164:167], v161 offset:6144
	ds_read_b128 v[168:171], v162 offset:4096
	ds_read_b128 v[192:195], v162 offset:6144
	s_waitcnt lgkmcnt(3)
	v_mfma_f32_16x16x32_bf16 v[196:199], v[40:43], v[0:3], 0
	v_mfma_f32_16x16x32_bf16 v[40:43], v[40:43], v[8:11], 0
	s_waitcnt lgkmcnt(2)
	v_mfma_f32_16x16x32_bf16 v[200:203], v[164:167], v[0:3], 0
	v_mfma_f32_16x16x32_bf16 v[162:165], v[164:167], v[8:11], 0
	s_waitcnt lgkmcnt(1)
	v_mfma_f32_16x16x32_bf16 v[196:199], v[168:171], v[4:7], v[196:199]
	v_mfma_f32_16x16x32_bf16 v[40:43], v[168:171], v[12:15], v[40:43]
	s_waitcnt lgkmcnt(0)
	v_mfma_f32_16x16x32_bf16 v[166:169], v[192:195], v[4:7], v[200:203]
	v_mfma_f32_16x16x32_bf16 v[192:195], v[192:195], v[12:15], v[162:165]
	v_add_u32_e32 v29, 0xfffffe00, v160
	v_max_i32_e32 v29, 0, v29
	v_lshl_add_u32 v29, v29, 2, v181
	ds_read2st64_b32 v[30:31], v29 offset0:132 offset1:197
	v_add_u32_e32 v45, 0xfffffde0, v160
	v_add_u32_e32 v161, 0xfffffd00, v160
	v_max_i32_e32 v45, 0, v45
	v_max_i32_e32 v161, 0, v161
	s_waitcnt lgkmcnt(0)
	v_fmamk_f32 v29, v196, 0x3e38aa3b, v30
	v_add_u32_e32 v30, 0xfffffdf0, v160
	v_max_i32_e32 v30, 0, v30
	v_lshl_add_u32 v30, v30, 2, v181
	ds_read2st64_b32 v[46:47], v30 offset0:132 offset1:197
	v_lshl_add_u32 v45, v45, 2, v181
	v_lshl_add_u32 v161, v161, 2, v181
	ds_read2st64_b32 v[170:171], v45 offset0:132 offset1:197
	ds_read2st64_b32 v[202:203], v161 offset0:132 offset1:197
	s_waitcnt lgkmcnt(2)
	v_fmamk_f32 v30, v197, 0x3e38aa3b, v46
	v_add_u32_e32 v46, 0xfffffdd0, v160
	v_max_i32_e32 v46, 0, v46
	v_lshl_add_u32 v46, v46, 2, v181
	ds_read2st64_b32 v[200:201], v46 offset0:132 offset1:197
	v_add_u32_e32 v161, 0xfffffcf0, v160
	v_max_i32_e32 v161, 0, v161
	v_lshl_add_u32 v161, v161, 2, v181
	ds_read2st64_b32 v[204:205], v161 offset0:132 offset1:197
	v_add_u32_e32 v161, 0xfffffce0, v160
	v_add_u32_e32 v160, 0xfffffcd0, v160
	v_max_i32_e32 v161, 0, v161
	v_max_i32_e32 v160, 0, v160
	v_lshl_add_u32 v161, v161, 2, v181
	v_lshl_add_u32 v160, v160, 2, v181
	v_sub_f32_e32 v29, v29, v154
	s_waitcnt lgkmcnt(3)
	v_fmac_f32_e32 v171, 0x3e38aa3b, v42
	s_waitcnt lgkmcnt(1)
	v_fmac_f32_e32 v201, 0x3e38aa3b, v43
	ds_read2st64_b32 v[206:207], v161 offset0:132 offset1:197
	ds_read2st64_b32 v[208:209], v160 offset0:132 offset1:197
	v_exp_f32_e32 v160, v29
	v_sub_f32_e32 v29, v30, v154
	v_fmac_f32_e32 v31, 0x3e38aa3b, v40
	v_fmac_f32_e32 v47, 0x3e38aa3b, v41
	v_sub_f32_e32 v40, v171, v155
	v_sub_f32_e32 v41, v201, v155
	v_exp_f32_e32 v161, v29
	v_exp_f32_e32 v40, v40
	v_exp_f32_e32 v41, v41
	v_fmamk_f32 v45, v198, 0x3e38aa3b, v170
	v_fmamk_f32 v46, v199, 0x3e38aa3b, v200
	v_sub_f32_e32 v29, v45, v154
	v_fmac_f32_e32 v203, 0x3e38aa3b, v192
	s_waitcnt lgkmcnt(2)
	v_fmac_f32_e32 v205, 0x3e38aa3b, v193
	v_fmamk_f32 v162, v166, 0x3e38aa3b, v202
	v_fmamk_f32 v163, v167, 0x3e38aa3b, v204
	s_waitcnt lgkmcnt(1)
; template <int MODE>
; __device__ __forceinline__ void nsa_compute(int cur, int buf, int t, int hl, u64 mymask, const bf16x8 (&Qf)[2][2], f32x4 (&O)[4][2], float (&m)[2], float (&l)[2],
;                                             const float (&inv)[2], float* impw, char* lds) {
;     ...
;       float pv[2][4];
;       if (MODE == 1) {
; #pragma unroll
;         for (int kk = 0; kk < 2; ++kk)
; #pragma unroll
;           for (int e = 0; e < 4; ++e) pv[kk][e] = __builtin_amdgcn_exp2f(sv[kk][e] - m[r]) * inv[r];
; #pragma unroll
;         for (int kk = 0; kk < 2; ++kk) { g1s[kk] += pv[kk][0] + pv[kk][1] + pv[kk][2] + 0.5f * pv[kk][3]; p3s[kk] += 0.5f * pv[kk][3]; }
;       } else {
;         const float mxa = fmaxf(fmaxf(sv[0][0], sv[0][1]), sv[0][2]), mxb = fmaxf(fmaxf(sv[0][3], sv[1][0]), sv[1][1]);
;         float mx = fmaxf(fmaxf(fmaxf(sv[1][2], sv[1][3]), mxa), mxb);
;         if (MODE == 2) mx = selok ? mx : -__builtin_inff();
;         if (__any(mx > m[r] + 8.0f)) {
;           mx = fmaxf(mx, __shfl_xor(mx, 16)); mx = fmaxf(mx, __shfl_xor(mx, 32));
;           const float mn = fmaxf(m[r], mx), al = __builtin_amdgcn_exp2f(m[r] - mn);
;           m[r] = mn; l[r] *= al;
;           if (MODE != 0) {
; #pragma unroll
;             for (int df = 0; df < 4; ++df) O[df][r] *= al;
;           }
;         }
;         const float me = (MODE == 2) ? (selok ? m[r] : __builtin_inff()) : m[r];
;         float ps = 0.f;
; #pragma unroll
;         for (int kk = 0; kk < 2; ++kk)
; #pragma unroll
;           for (int e = 0; e < 4; ++e) { pv[kk][e] = __builtin_amdgcn_exp2f(sv[kk][e] - me); ps += pv[kk][e]; }
;         l[r] += ps;
;       }
;       if (MODE != 0) {
;         const unsigned w0 = pk2(pv[0][0], pv[0][1]), w1 = pk2(pv[0][2], pv[0][3]), w2 = pk2(pv[1][0], pv[1][1]), w3 = pk2(pv[1][2], pv[1][3]);
;         u32x4 pw; pw.x = w0; pw.y = w1; pw.z = w2; pw.w = w3;
;         Pf[r] = __builtin_bit_cast(bf16x8, pw);
;       }
;     }
;     if (MODE != 0) {
;       bf16x8 vfr[4];
; #pragma unroll
;       for (int df = 0; df < 4; ++df) {
;         const bf16x4 va = *(const bf16x4*)(vt + (df * 16 + fr) * 68 + 32 * s2 + 4 * fq);
;         const bf16x4 vb = *(const bf16x4*)(vt + (df * 16 + fr) * 68 + 32 * s2 + 16 + 4 * fq);
;         bf16x8 vf; vf[0] = va[0]; vf[1] = va[1]; vf[2] = va[2]; vf[3] = va[3]; vf[4] = vb[0]; vf[5] = vb[1]; vf[6] = vb[2]; vf[7] = vb[3];
	v_fmamk_f32 v164, v168, 0x3e38aa3b, v206
	s_waitcnt lgkmcnt(0)
	v_fmamk_f32 v165, v169, 0x3e38aa3b, v208
	v_pk_mul_f32 v[166:167], v[156:157], v[160:161]
	v_exp_f32_e32 v160, v29
	v_sub_f32_e32 v29, v46, v154
	v_pk_mul_f32 v[168:169], v[158:159], v[40:41]
	v_sub_f32_e32 v40, v203, v155
	v_sub_f32_e32 v41, v205, v155
	v_exp_f32_e32 v161, v29
	v_sub_f32_e32 v29, v162, v154
	v_exp_f32_e32 v40, v40
	v_exp_f32_e32 v41, v41
	v_exp_f32_e32 v162, v29
	v_sub_f32_e32 v29, v163, v154
	v_exp_f32_e32 v163, v29
	v_sub_f32_e32 v29, v164, v154
	v_exp_f32_e32 v164, v29
	v_sub_f32_e32 v29, v165, v154
	v_fmac_f32_e32 v207, 0x3e38aa3b, v194
	v_fmac_f32_e32 v209, 0x3e38aa3b, v195
	v_sub_f32_e32 v30, v31, v155
	v_sub_f32_e32 v31, v47, v155
	v_exp_f32_e32 v165, v29
	v_add_f32_e32 v29, v166, v167
	v_cvt_pk_bf16_f32 v196, v166, v167
	v_exp_f32_e32 v30, v30
	v_exp_f32_e32 v31, v31
	v_pk_mul_f32 v[166:167], v[158:159], v[40:41]
	v_sub_f32_e32 v40, v207, v155
	v_sub_f32_e32 v41, v209, v155
	v_exp_f32_e32 v40, v40
	v_exp_f32_e32 v41, v41
	v_pk_mul_f32 v[160:161], v[156:157], v[160:161]
	v_pk_mul_f32 v[30:31], v[158:159], v[30:31]
	v_add_f32_e32 v29, v160, v29
	v_pk_mul_f32 v[170:171], v[158:159], v[40:41]
	v_add_f32_e32 v40, v30, v31
	v_fmac_f32_e32 v29, 0.5, v161
	v_add_f32_e32 v40, v168, v40
	v_add_f32_e32 v29, 0, v29
	v_fmac_f32_e32 v40, 0.5, v169
	v_cvt_pk_bf16_f32 v197, v160, v161
	v_add_f32_e32 v160, v29, v40
	v_cvt_pk_bf16_f32 v192, v30, v31
	ds_read2_b64 v[28:31], v28 offset0:8 offset1:12
	ds_read2_b64 v[200:203], v44 offset0:24 offset1:28
	ds_read2_b64 v[204:207], v189 offset0:40 offset1:44
	ds_read2_b64 v[236:239], v190 offset0:56 offset1:60
	v_pk_mul_f32 v[162:163], v[156:157], v[162:163]
	v_pk_mul_f32 v[164:165], v[156:157], v[164:165]
	v_cvt_pk_bf16_f32 v198, v162, v163
	v_cvt_pk_bf16_f32 v199, v164, v165
	v_cvt_pk_bf16_f32 v193, v168, v169
	v_cvt_pk_bf16_f32 v194, v166, v167
	v_cvt_pk_bf16_f32 v195, v170, v171
	s_waitcnt lgkmcnt(3)
	v_mfma_f32_16x16x32_bf16 v[44:47], v[28:31], v[196:199], v[16:19]
	v_mfma_f32_16x16x32_bf16 v[28:31], v[28:31], v[192:195], v[20:23]
	s_waitcnt lgkmcnt(2)
	v_mfma_f32_16x16x32_bf16 v[40:43], v[200:203], v[196:199], v[24:27]
	v_mfma_f32_16x16x32_bf16 v[24:27], v[200:203], v[192:195], v[32:35]
	s_waitcnt lgkmcnt(1)
	v_mfma_f32_16x16x32_bf16 v[36:39], v[204:207], v[196:199], v[36:39]
	v_mfma_f32_16x16x32_bf16 v[20:23], v[204:207], v[192:195], v[136:139]
	s_waitcnt lgkmcnt(0)
	v_mfma_f32_16x16x32_bf16 v[32:35], v[236:239], v[196:199], v[140:143]
	v_mfma_f32_16x16x32_bf16 v[16:19], v[236:239], v[192:195], v[144:147]
	ds_add_f32 v185, v160 offset:32
	v_or_b32_e32 v136, 8, v176
	v_cmp_gt_u32_e32 vcc, 63, v136
	s_and_saveexec_b64 s[16:17], vcc
	v_mul_f32_e32 v136, 0.5, v161
	v_mul_f32_e32 v137, 0.5, v169
	v_add_f32_e32 v136, 0, v136
	v_add_f32_e32 v136, v136, v137
	ds_add_f32 v185, v136 offset:36
	s_or_b64 exec, exec, s[16:17]
	v_add_f32_e32 v136, v162, v163
	v_add_f32_e32 v136, v164, v136
	v_add_f32_e32 v137, v166, v167
	v_fmac_f32_e32 v136, 0.5, v165
	v_add_f32_e32 v137, v170, v137
	v_add_f32_e32 v136, 0, v136
	v_fmac_f32_e32 v137, 0.5, v171
	v_add_f32_e32 v136, v136, v137
	ds_add_f32 v185, v136 offset:48
	v_or_b32_e32 v136, 12, v176
	v_cmp_gt_u32_e32 vcc, 63, v136
	s_and_saveexec_b64 s[16:17], vcc
	v_mul_f32_e32 v136, 0.5, v165
	v_mul_f32_e32 v137, 0.5, v171
	v_add_f32_e32 v136, 0, v136
	v_add_f32_e32 v136, v136, v137
	ds_add_f32 v185, v136 offset:52
	s_or_b64 exec, exec, s[16:17]
	s_cmp_lt_i32 s69, 0
	s_cbranch_scc1 .LBB0_326
	v_mov_b32 v136, v179
	s_nop 0
	v_ashrrev_i32_e32 v137, 3, v136
	v_xor_b32_e32 v139, v137, v136
	v_lshlrev_b32_e32 v136, 3, v136
	v_lshlrev_b32_e32 v139, 4, v139
	v_and_b32_e32 v136, 56, v136
	v_lshlrev_b32_e32 v138, 7, v137
	v_and_b32_e32 v139, 0x70, v139
	v_mul_u32_u24_e32 v136, 0x88, v136
	v_lshlrev_b32_e32 v137, 1, v137
	v_add3_u32 v138, s73, v138, v139
	v_add3_u32 v136, s72, v136, v137
	ds_write_b128 v138, v[48:51]
	ds_write_b16 v136, v52 offset:16384
	ds_write_b16_d16_hi v136, v52 offset:16520
	ds_write_b16 v136, v53 offset:16656
	ds_write_b16_d16_hi v136, v53 offset:16792
	ds_write_b16 v136, v54 offset:16928
	ds_write_b16_d16_hi v136, v54 offset:17064
	ds_write_b16 v136, v55 offset:17200
	ds_write_b16_d16_hi v136, v55 offset:17336

; #define HBLK (opaque_tid() >> 8)
; __device__ __forceinline__ void mixB2_item(int idx, const bf16_t* z, const float* hsl, const float* Pc, const float* carryP, const float* carryH, bf16_t* y) {
;   const int c = idx & 63, g = (idx >> 6) & 3, b = idx >> 8;
;   const int q = HTID >> 6, j = HTID & 63;
; __device__ __forceinline__ void run_phase(const Params& P, int ph, char* lds) {
;     ...
;       const int hb = HBLK;
;       for (int it = blockIdx.x * 2 + hb; it < 2048; it += gridDim.x * 2) mixB2_item(it, big, hsl, Pc, carryP, carryH, abuf);
.LBB0_498:
	s_setprio 0
	v_mov_b32 v0, v179
	v_readlane_b32 s0, v253, 3
	v_ashrrev_i32_e32 v1, 8, v0
	s_nop 0
	v_add_u32_e32 v20, s0, v1
	s_movk_i32 s0, 0x800
	v_cmp_gt_i32_e32 vcc, s0, v20
	s_and_saveexec_b64 s[30:31], vcc
	s_cbranch_execz .LBB0_537
	v_lshrrev_b32_e32 v0, 8, v0
	v_readlane_b32 s0, v253, 3
	s_mov_b64 s[34:35], 0
	s_nop 0
	v_add_u16_e32 v21, s0, v0
